# v18 plus LDS-DMA issued in SGPR-base + 32-bit VGPR-offset form in 9 GEMM K loops: all 16 per-iteration v_lshl_add_u64 address adds removed, two derived bases kept in s98-s101 by SALU
# speedup vs baseline: 1.0056x; 1.0036x over previous
.Lsp_skip0:
.LBB0_233:
	ds_read_b128 v[162:165], v155
	ds_read_b128 v[166:169], v155 offset:1024
	ds_read_b128 v[170:173], v155 offset:2048
	ds_read_b128 v[174:177], v155 offset:3072
	ds_read_b128 v[178:181], v158
	ds_read_b128 v[182:185], v158 offset:1024
	ds_read_b128 v[186:189], v158 offset:2048
	ds_read_b128 v[190:193], v158 offset:3072
	ds_read_b128 v[194:197], v159
	ds_read_b128 v[198:201], v159 offset:1024
	ds_read_b128 v[202:205], v159 offset:2048
	ds_read_b128 v[206:209], v159 offset:3072
	ds_read_b128 v[210:213], v159 offset:4096
	ds_read_b128 v[214:217], v159 offset:5120
	ds_read_b128 v[218:221], v159 offset:6144
	ds_read_b128 v[222:225], v159 offset:7168
	s_add_u32 s36, s34, 0xfff00080
	s_addc_u32 s37, s35, -1
	s_cmp_eq_u32 s68, 60
	s_cselect_b32 s39, s25, s37
	s_cselect_b32 s38, s64, s36
	s_cselect_b32 s37, s23, s67
	s_cselect_b32 s36, s65, s66
	s_add_i32 m0, s31, 0xc000
	s_nop 0
	global_load_lds_dwordx4 v138, s[34:35]
	s_add_i32 m0, s31, 0xe000
	s_nop 0
	global_load_lds_dwordx4 v136, s[34:35]
	s_waitcnt vmcnt(8)
	s_waitcnt lgkmcnt(0)
	s_barrier
	s_waitcnt lgkmcnt(0)
	v_mfma_f32_16x16x32_bf16 v[124:127], v[162:165], v[194:197], v[124:127]
	v_mfma_f32_16x16x32_bf16 v[120:123], v[170:173], v[194:197], v[120:123]
	v_mfma_f32_16x16x32_bf16 v[108:111], v[162:165], v[202:205], v[108:111]
	v_mfma_f32_16x16x32_bf16 v[104:107], v[170:173], v[202:205], v[104:107]
	s_add_u32 s98, s36, s12
	s_addc_u32 s99, s37, s13
	s_add_i32 s69, s57, s40
	v_mfma_f32_16x16x32_bf16 v[92:95], v[162:165], v[210:213], v[92:95]
	s_add_u32 s100, s38, s12
	s_addc_u32 s101, s39, s13
	v_mfma_f32_16x16x32_bf16 v[88:91], v[170:173], v[210:213], v[88:91]
	v_mfma_f32_16x16x32_bf16 v[76:79], v[162:165], v[218:221], v[76:79]
	v_mfma_f32_16x16x32_bf16 v[72:75], v[170:173], v[218:221], v[72:75]
	s_add_u32 s70, s36, 0x100000
	v_mfma_f32_16x16x32_bf16 v[124:127], v[166:169], v[198:201], v[124:127]
	v_mfma_f32_16x16x32_bf16 v[120:123], v[174:177], v[198:201], v[120:123]
	v_mfma_f32_16x16x32_bf16 v[108:111], v[166:169], v[206:209], v[108:111]
	v_mfma_f32_16x16x32_bf16 v[104:107], v[174:177], v[206:209], v[104:107]
	s_addc_u32 s71, s37, 0
	v_mfma_f32_16x16x32_bf16 v[92:95], v[166:169], v[214:217], v[92:95]
	v_mfma_f32_16x16x32_bf16 v[88:91], v[174:177], v[214:217], v[88:91]
	v_mfma_f32_16x16x32_bf16 v[76:79], v[166:169], v[222:225], v[76:79]
	v_mfma_f32_16x16x32_bf16 v[72:75], v[174:177], v[222:225], v[72:75]
	v_mfma_f32_16x16x32_bf16 v[116:119], v[178:181], v[194:197], v[116:119]
	v_mfma_f32_16x16x32_bf16 v[112:115], v[186:189], v[194:197], v[112:115]
	v_mfma_f32_16x16x32_bf16 v[100:103], v[178:181], v[202:205], v[100:103]
	v_mfma_f32_16x16x32_bf16 v[96:99], v[186:189], v[202:205], v[96:99]
	v_mfma_f32_16x16x32_bf16 v[84:87], v[178:181], v[210:213], v[84:87]
	v_mfma_f32_16x16x32_bf16 v[80:83], v[186:189], v[210:213], v[80:83]
	v_mfma_f32_16x16x32_bf16 v[68:71], v[178:181], v[218:221], v[68:71]
	v_mfma_f32_16x16x32_bf16 v[64:67], v[186:189], v[218:221], v[64:67]
	v_mfma_f32_16x16x32_bf16 v[116:119], v[182:185], v[198:201], v[116:119]
	v_mfma_f32_16x16x32_bf16 v[112:115], v[190:193], v[198:201], v[112:115]
	v_mfma_f32_16x16x32_bf16 v[100:103], v[182:185], v[206:209], v[100:103]
	v_mfma_f32_16x16x32_bf16 v[96:99], v[190:193], v[206:209], v[96:99]
	v_mfma_f32_16x16x32_bf16 v[84:87], v[182:185], v[214:217], v[84:87]
	v_mfma_f32_16x16x32_bf16 v[80:83], v[190:193], v[214:217], v[80:83]
	v_mfma_f32_16x16x32_bf16 v[68:71], v[182:185], v[222:225], v[68:71]
	v_mfma_f32_16x16x32_bf16 v[64:67], v[190:193], v[222:225], v[64:67]
	s_barrier
	ds_read_b128 v[194:197], v159 offset:16384
	ds_read_b128 v[198:201], v159 offset:17408
	ds_read_b128 v[202:205], v159 offset:18432
	ds_read_b128 v[206:209], v159 offset:19456
	ds_read_b128 v[210:213], v159 offset:20480
	ds_read_b128 v[214:217], v159 offset:21504
	ds_read_b128 v[218:221], v159 offset:22528
	ds_read_b128 v[222:225], v159 offset:23552
	s_mov_b32 m0, s69
	s_nop 0
	global_load_lds_dwordx4 v130, s[36:37]
	s_add_i32 m0, s69, 0x2000
	s_add_i32 s69, s58, s40
	global_load_lds_dwordx4 v134, s[36:37]
	s_mov_b32 m0, s69
	s_nop 0
	global_load_lds_dwordx4 v130, s[70:71]
	s_add_i32 m0, s69, 0x2000
	s_nop 0
	global_load_lds_dwordx4 v134, s[70:71]
	s_mov_b32 m0, s31
	s_nop 0
	global_load_lds_dwordx4 v128, s[38:39]
	s_mov_b32 m0, s50
	s_nop 0
	global_load_lds_dwordx4 v132, s[38:39]
	s_waitcnt vmcnt(8)
	s_waitcnt lgkmcnt(0)
	s_barrier
	s_waitcnt lgkmcnt(0)
	v_mfma_f32_16x16x32_bf16 v[60:63], v[162:165], v[194:197], v[60:63]
	v_mfma_f32_16x16x32_bf16 v[56:59], v[170:173], v[194:197], v[56:59]
	v_mfma_f32_16x16x32_bf16 v[48:51], v[162:165], v[202:205], v[48:51]
	v_mfma_f32_16x16x32_bf16 v[40:43], v[170:173], v[202:205], v[40:43]
	s_add_i32 s69, 0, 0x18000
	v_mfma_f32_16x16x32_bf16 v[32:35], v[162:165], v[210:213], v[32:35]
	v_mfma_f32_16x16x32_bf16 v[24:27], v[170:173], v[210:213], v[24:27]
	v_add_u32_e32 v146, s69, v149
	v_mfma_f32_16x16x32_bf16 v[16:19], v[162:165], v[218:221], v[16:19]
	v_mfma_f32_16x16x32_bf16 v[8:11], v[170:173], v[218:221], v[8:11]
	s_add_i32 s70, 0, 0x1c000
	v_mfma_f32_16x16x32_bf16 v[60:63], v[166:169], v[198:201], v[60:63]
	v_mfma_f32_16x16x32_bf16 v[56:59], v[174:177], v[198:201], v[56:59]
	s_add_u32 s38, s38, 0x100000
	v_mfma_f32_16x16x32_bf16 v[48:51], v[166:169], v[206:209], v[48:51]
	v_mfma_f32_16x16x32_bf16 v[40:43], v[174:177], v[206:209], v[40:43]
	s_addc_u32 s39, s39, 0
	v_mfma_f32_16x16x32_bf16 v[32:35], v[166:169], v[214:217], v[32:35]
	v_mfma_f32_16x16x32_bf16 v[24:27], v[174:177], v[214:217], v[24:27]
	v_mfma_f32_16x16x32_bf16 v[16:19], v[166:169], v[222:225], v[16:19]
	v_mfma_f32_16x16x32_bf16 v[8:11], v[174:177], v[222:225], v[8:11]
	v_mfma_f32_16x16x32_bf16 v[52:55], v[178:181], v[194:197], v[52:55]
	v_mfma_f32_16x16x32_bf16 v[44:47], v[186:189], v[194:197], v[44:47]
	v_mfma_f32_16x16x32_bf16 v[36:39], v[178:181], v[202:205], v[36:39]
	v_mfma_f32_16x16x32_bf16 v[28:31], v[186:189], v[202:205], v[28:31]
	v_mfma_f32_16x16x32_bf16 v[20:23], v[178:181], v[210:213], v[20:23]
	v_mfma_f32_16x16x32_bf16 v[12:15], v[186:189], v[210:213], v[12:15]
	v_mfma_f32_16x16x32_bf16 v[4:7], v[178:181], v[218:221], v[4:7]
	v_mfma_f32_16x16x32_bf16 v[0:3], v[186:189], v[218:221], v[0:3]
	v_mfma_f32_16x16x32_bf16 v[52:55], v[182:185], v[198:201], v[52:55]
	v_mfma_f32_16x16x32_bf16 v[44:47], v[190:193], v[198:201], v[44:47]
	v_mfma_f32_16x16x32_bf16 v[36:39], v[182:185], v[206:209], v[36:39]
	v_mfma_f32_16x16x32_bf16 v[28:31], v[190:193], v[206:209], v[28:31]
	v_mfma_f32_16x16x32_bf16 v[20:23], v[182:185], v[214:217], v[20:23]
	v_mfma_f32_16x16x32_bf16 v[12:15], v[190:193], v[214:217], v[12:15]
	v_mfma_f32_16x16x32_bf16 v[4:7], v[182:185], v[222:225], v[4:7]
	v_mfma_f32_16x16x32_bf16 v[0:3], v[190:193], v[222:225], v[0:3]
	s_barrier
	ds_read_b128 v[194:197], v159 offset:32768
	ds_read_b128 v[198:201], v159 offset:33792
	ds_read_b128 v[202:205], v159 offset:34816
	ds_read_b128 v[206:209], v159 offset:35840
	ds_read_b128 v[210:213], v159 offset:36864
	ds_read_b128 v[214:217], v159 offset:37888
	ds_read_b128 v[218:221], v159 offset:38912
	ds_read_b128 v[222:225], v159 offset:39936
	ds_read_b128 v[162:165], v146
	ds_read_b128 v[166:169], v146 offset:1024
	ds_read_b128 v[170:173], v146 offset:2048
	ds_read_b128 v[174:177], v146 offset:3072
	v_add_u32_e32 v146, s70, v149
	ds_read_b128 v[178:181], v146
	ds_read_b128 v[182:185], v146 offset:1024
	ds_read_b128 v[186:189], v146 offset:2048
	ds_read_b128 v[190:193], v146 offset:3072
	s_mov_b32 m0, s51
	s_nop 0
	global_load_lds_dwordx4 v128, s[38:39]
	s_mov_b32 m0, s52
	s_nop 0
	global_load_lds_dwordx4 v132, s[38:39]
	s_waitcnt vmcnt(8)
	s_waitcnt lgkmcnt(0)
	s_barrier
	s_waitcnt lgkmcnt(0)
	v_mfma_f32_16x16x32_bf16 v[124:127], v[162:165], v[194:197], v[124:127]
	v_mfma_f32_16x16x32_bf16 v[120:123], v[170:173], v[194:197], v[120:123]
	v_mfma_f32_16x16x32_bf16 v[108:111], v[162:165], v[202:205], v[108:111]
	v_mfma_f32_16x16x32_bf16 v[104:107], v[170:173], v[202:205], v[104:107]
	s_add_i32 s38, s69, s40
	v_mfma_f32_16x16x32_bf16 v[92:95], v[162:165], v[210:213], v[92:95]
	v_mfma_f32_16x16x32_bf16 v[88:91], v[170:173], v[210:213], v[88:91]
	v_mfma_f32_16x16x32_bf16 v[76:79], v[162:165], v[218:221], v[76:79]
	v_mfma_f32_16x16x32_bf16 v[72:75], v[170:173], v[218:221], v[72:75]
	s_add_u32 s36, s36, 0x100080
	v_mfma_f32_16x16x32_bf16 v[124:127], v[166:169], v[198:201], v[124:127]
	v_mfma_f32_16x16x32_bf16 v[120:123], v[174:177], v[198:201], v[120:123]
	v_mfma_f32_16x16x32_bf16 v[108:111], v[166:169], v[206:209], v[108:111]
	v_mfma_f32_16x16x32_bf16 v[104:107], v[174:177], v[206:209], v[104:107]
	s_addc_u32 s37, s37, 0
	v_mfma_f32_16x16x32_bf16 v[92:95], v[166:169], v[214:217], v[92:95]
	v_mfma_f32_16x16x32_bf16 v[88:91], v[174:177], v[214:217], v[88:91]
	v_mfma_f32_16x16x32_bf16 v[76:79], v[166:169], v[222:225], v[76:79]
	v_mfma_f32_16x16x32_bf16 v[72:75], v[174:177], v[222:225], v[72:75]
	v_mfma_f32_16x16x32_bf16 v[116:119], v[178:181], v[194:197], v[116:119]
	v_mfma_f32_16x16x32_bf16 v[112:115], v[186:189], v[194:197], v[112:115]
	v_mfma_f32_16x16x32_bf16 v[100:103], v[178:181], v[202:205], v[100:103]
	v_mfma_f32_16x16x32_bf16 v[96:99], v[186:189], v[202:205], v[96:99]
	v_mfma_f32_16x16x32_bf16 v[84:87], v[178:181], v[210:213], v[84:87]
	v_mfma_f32_16x16x32_bf16 v[80:83], v[186:189], v[210:213], v[80:83]
	v_mfma_f32_16x16x32_bf16 v[68:71], v[178:181], v[218:221], v[68:71]
	v_mfma_f32_16x16x32_bf16 v[64:67], v[186:189], v[218:221], v[64:67]
	v_mfma_f32_16x16x32_bf16 v[116:119], v[182:185], v[198:201], v[116:119]
	v_mfma_f32_16x16x32_bf16 v[112:115], v[190:193], v[198:201], v[112:115]
	v_mfma_f32_16x16x32_bf16 v[100:103], v[182:185], v[206:209], v[100:103]
	v_mfma_f32_16x16x32_bf16 v[96:99], v[190:193], v[206:209], v[96:99]
	v_mfma_f32_16x16x32_bf16 v[84:87], v[182:185], v[214:217], v[84:87]
	v_mfma_f32_16x16x32_bf16 v[80:83], v[190:193], v[214:217], v[80:83]
	v_mfma_f32_16x16x32_bf16 v[68:71], v[182:185], v[222:225], v[68:71]
	v_mfma_f32_16x16x32_bf16 v[64:67], v[190:193], v[222:225], v[64:67]
	s_barrier
	ds_read_b128 v[194:197], v159 offset:49152
	ds_read_b128 v[198:201], v159 offset:50176
	ds_read_b128 v[202:205], v159 offset:51200
	ds_read_b128 v[206:209], v159 offset:52224
	ds_read_b128 v[210:213], v159 offset:53248
	ds_read_b128 v[214:217], v159 offset:54272
	ds_read_b128 v[218:221], v159 offset:55296
	ds_read_b128 v[222:225], v159 offset:56320
	s_mov_b32 m0, s38
	s_nop 0
	global_load_lds_dwordx4 v130, s[98:99]
	s_add_i32 m0, s38, 0x2000
	s_add_i32 s38, s70, s40
	global_load_lds_dwordx4 v134, s[98:99]
	s_mov_b32 m0, s38
	s_nop 0
	global_load_lds_dwordx4 v130, s[36:37]
	s_add_i32 m0, s38, 0x2000
	s_nop 0
	global_load_lds_dwordx4 v134, s[36:37]
	s_mov_b32 m0, s54
	s_nop 0
	global_load_lds_dwordx4 v128, s[100:101]
	s_mov_b32 m0, s55
	s_nop 0
	global_load_lds_dwordx4 v132, s[100:101]
	s_waitcnt vmcnt(8)
	s_waitcnt lgkmcnt(0)
	s_barrier
	s_waitcnt lgkmcnt(0)
	v_mfma_f32_16x16x32_bf16 v[60:63], v[162:165], v[194:197], v[60:63]
	v_mfma_f32_16x16x32_bf16 v[56:59], v[170:173], v[194:197], v[56:59]
	v_mfma_f32_16x16x32_bf16 v[48:51], v[162:165], v[202:205], v[48:51]
	v_mfma_f32_16x16x32_bf16 v[40:43], v[170:173], v[202:205], v[40:43]
	v_mfma_f32_16x16x32_bf16 v[32:35], v[162:165], v[210:213], v[32:35]
	v_mfma_f32_16x16x32_bf16 v[24:27], v[170:173], v[210:213], v[24:27]
	v_mfma_f32_16x16x32_bf16 v[16:19], v[162:165], v[218:221], v[16:19]
	v_mfma_f32_16x16x32_bf16 v[8:11], v[170:173], v[218:221], v[8:11]
	v_mfma_f32_16x16x32_bf16 v[60:63], v[166:169], v[198:201], v[60:63]
	v_mfma_f32_16x16x32_bf16 v[56:59], v[174:177], v[198:201], v[56:59]
	v_mfma_f32_16x16x32_bf16 v[48:51], v[166:169], v[206:209], v[48:51]
	v_mfma_f32_16x16x32_bf16 v[40:43], v[174:177], v[206:209], v[40:43]
	v_mfma_f32_16x16x32_bf16 v[32:35], v[166:169], v[214:217], v[32:35]
	v_mfma_f32_16x16x32_bf16 v[24:27], v[174:177], v[214:217], v[24:27]
	v_mfma_f32_16x16x32_bf16 v[16:19], v[166:169], v[222:225], v[16:19]
	v_mfma_f32_16x16x32_bf16 v[8:11], v[174:177], v[222:225], v[8:11]
	v_mfma_f32_16x16x32_bf16 v[52:55], v[178:181], v[194:197], v[52:55]
	v_mfma_f32_16x16x32_bf16 v[44:47], v[186:189], v[194:197], v[44:47]
	v_mfma_f32_16x16x32_bf16 v[36:39], v[178:181], v[202:205], v[36:39]
	v_mfma_f32_16x16x32_bf16 v[28:31], v[186:189], v[202:205], v[28:31]
	v_mfma_f32_16x16x32_bf16 v[20:23], v[178:181], v[210:213], v[20:23]
	v_mfma_f32_16x16x32_bf16 v[12:15], v[186:189], v[210:213], v[12:15]
	v_mfma_f32_16x16x32_bf16 v[4:7], v[178:181], v[218:221], v[4:7]
	v_mfma_f32_16x16x32_bf16 v[0:3], v[186:189], v[218:221], v[0:3]
	v_mfma_f32_16x16x32_bf16 v[52:55], v[182:185], v[198:201], v[52:55]
	v_mfma_f32_16x16x32_bf16 v[44:47], v[190:193], v[198:201], v[44:47]
	v_mfma_f32_16x16x32_bf16 v[36:39], v[182:185], v[206:209], v[36:39]
	v_mfma_f32_16x16x32_bf16 v[28:31], v[190:193], v[206:209], v[28:31]
	v_mfma_f32_16x16x32_bf16 v[20:23], v[182:185], v[214:217], v[20:23]
	v_mfma_f32_16x16x32_bf16 v[12:15], v[190:193], v[214:217], v[12:15]
	v_mfma_f32_16x16x32_bf16 v[4:7], v[182:185], v[222:225], v[4:7]
	v_mfma_f32_16x16x32_bf16 v[0:3], v[190:193], v[222:225], v[0:3]
	s_barrier
	s_add_i32 s68, s68, 2
	s_add_u32 s66, s66, 0x100
	s_addc_u32 s67, s67, 0
	s_add_u32 s34, s34, 0x100
	s_addc_u32 s35, s35, 0
	s_cmp_gt_u32 s68, 61
	s_cbranch_scc0 .LBB0_233
	s_setprio 0
	s_and_b64 vcc, exec, s[14:15]
	s_cbranch_vccz .LBB0_236
	s_barrier

.Lsp_skip1:
.LBB0_254:
	ds_read_b128 v[152:155], v149
	ds_read_b128 v[156:159], v149 offset:1024
	ds_read_b128 v[160:163], v149 offset:2048
	ds_read_b128 v[164:167], v149 offset:3072
	ds_read_b128 v[168:171], v150
	ds_read_b128 v[172:175], v150 offset:1024
	ds_read_b128 v[176:179], v150 offset:2048
	ds_read_b128 v[180:183], v150 offset:3072
	ds_read_b128 v[184:187], v151
	ds_read_b128 v[188:191], v151 offset:1024
	ds_read_b128 v[192:195], v151 offset:2048
	ds_read_b128 v[196:199], v151 offset:3072
	ds_read_b128 v[200:203], v151 offset:4096
	ds_read_b128 v[204:207], v151 offset:5120
	ds_read_b128 v[208:211], v151 offset:6144
	ds_read_b128 v[212:215], v151 offset:7168
	s_add_u32 s26, s24, 0x100
	s_addc_u32 s27, s25, 0
	s_cmp_eq_u32 s67, 8
	s_cselect_b32 s31, s1, s27
	s_cselect_b32 s30, s0, s26
	s_cselect_b32 s29, s23, s66
	s_cselect_b32 s28, s22, s65
	s_add_i32 m0, s46, 0xc000
	s_nop 0
	global_load_lds_dwordx4 v138, s[24:25]
	s_add_i32 m0, s46, 0xe000
	s_nop 0
	global_load_lds_dwordx4 v136, s[24:25]
	s_waitcnt vmcnt(8)
	s_waitcnt lgkmcnt(0)
	s_barrier
	s_waitcnt lgkmcnt(0)
	v_mfma_f32_16x16x32_bf16 v[124:127], v[152:155], v[184:187], v[124:127]
	v_mfma_f32_16x16x32_bf16 v[120:123], v[160:163], v[184:187], v[120:123]
	v_mfma_f32_16x16x32_bf16 v[116:119], v[152:155], v[192:195], v[116:119]
	v_mfma_f32_16x16x32_bf16 v[108:111], v[160:163], v[192:195], v[108:111]
	s_add_u32 s98, s28, s10
	s_addc_u32 s99, s29, s11
	s_add_i32 s24, s55, s40
	v_mfma_f32_16x16x32_bf16 v[100:103], v[152:155], v[200:203], v[100:103]
	s_add_u32 s100, s30, s10
	s_addc_u32 s101, s31, s11
	v_mfma_f32_16x16x32_bf16 v[92:95], v[160:163], v[200:203], v[92:95]
	v_mfma_f32_16x16x32_bf16 v[84:87], v[152:155], v[208:211], v[84:87]
	v_mfma_f32_16x16x32_bf16 v[76:79], v[160:163], v[208:211], v[76:79]
	v_mfma_f32_16x16x32_bf16 v[124:127], v[156:159], v[188:191], v[124:127]
	v_mfma_f32_16x16x32_bf16 v[120:123], v[164:167], v[188:191], v[120:123]
	s_add_i32 s68, s56, s40
	v_mfma_f32_16x16x32_bf16 v[116:119], v[156:159], v[196:199], v[116:119]
	v_mfma_f32_16x16x32_bf16 v[108:111], v[164:167], v[196:199], v[108:111]
	v_mfma_f32_16x16x32_bf16 v[100:103], v[156:159], v[204:207], v[100:103]
	v_mfma_f32_16x16x32_bf16 v[92:95], v[164:167], v[204:207], v[92:95]
	v_mfma_f32_16x16x32_bf16 v[84:87], v[156:159], v[212:215], v[84:87]
	v_mfma_f32_16x16x32_bf16 v[76:79], v[164:167], v[212:215], v[76:79]
	v_mfma_f32_16x16x32_bf16 v[112:115], v[168:171], v[184:187], v[112:115]
	v_mfma_f32_16x16x32_bf16 v[104:107], v[176:179], v[184:187], v[104:107]
	v_mfma_f32_16x16x32_bf16 v[96:99], v[168:171], v[192:195], v[96:99]
	v_mfma_f32_16x16x32_bf16 v[88:91], v[176:179], v[192:195], v[88:91]
	v_mfma_f32_16x16x32_bf16 v[80:83], v[168:171], v[200:203], v[80:83]
	v_mfma_f32_16x16x32_bf16 v[72:75], v[176:179], v[200:203], v[72:75]
	v_mfma_f32_16x16x32_bf16 v[68:71], v[168:171], v[208:211], v[68:71]
	v_mfma_f32_16x16x32_bf16 v[64:67], v[176:179], v[208:211], v[64:67]
	v_mfma_f32_16x16x32_bf16 v[112:115], v[172:175], v[188:191], v[112:115]
	v_mfma_f32_16x16x32_bf16 v[104:107], v[180:183], v[188:191], v[104:107]
	v_mfma_f32_16x16x32_bf16 v[96:99], v[172:175], v[196:199], v[96:99]
	v_mfma_f32_16x16x32_bf16 v[88:91], v[180:183], v[196:199], v[88:91]
	v_mfma_f32_16x16x32_bf16 v[80:83], v[172:175], v[204:207], v[80:83]
	v_mfma_f32_16x16x32_bf16 v[72:75], v[180:183], v[204:207], v[72:75]
	v_mfma_f32_16x16x32_bf16 v[68:71], v[172:175], v[212:215], v[68:71]
	v_mfma_f32_16x16x32_bf16 v[64:67], v[180:183], v[212:215], v[64:67]
	s_barrier
	ds_read_b128 v[184:187], v151 offset:16384
	ds_read_b128 v[188:191], v151 offset:17408
	ds_read_b128 v[192:195], v151 offset:18432
	ds_read_b128 v[196:199], v151 offset:19456
	ds_read_b128 v[200:203], v151 offset:20480
	ds_read_b128 v[204:207], v151 offset:21504
	ds_read_b128 v[208:211], v151 offset:22528
	ds_read_b128 v[212:215], v151 offset:23552
	s_mov_b32 m0, s24
	s_nop 0
	global_load_lds_dwordx4 v132, s[28:29]
	s_add_i32 m0, s24, 0x2000
	s_add_u32 s24, s28, 0x30000
	s_addc_u32 s25, s29, 0
	global_load_lds_dwordx4 v128, s[28:29]
	s_mov_b32 m0, s68
	s_nop 0
	global_load_lds_dwordx4 v132, s[24:25]
	s_add_i32 m0, s68, 0x2000
	s_nop 0
	global_load_lds_dwordx4 v128, s[24:25]
	s_mov_b32 m0, s46
	s_nop 0
	global_load_lds_dwordx4 v134, s[30:31]
	s_mov_b32 m0, s47
	s_nop 0
	global_load_lds_dwordx4 v130, s[30:31]
	s_waitcnt vmcnt(8)
	s_waitcnt lgkmcnt(0)
	s_barrier
	s_waitcnt lgkmcnt(0)
	v_mfma_f32_16x16x32_bf16 v[60:63], v[152:155], v[184:187], v[60:63]
	v_mfma_f32_16x16x32_bf16 v[56:59], v[160:163], v[184:187], v[56:59]
	v_mfma_f32_16x16x32_bf16 v[52:55], v[152:155], v[192:195], v[52:55]
	v_mfma_f32_16x16x32_bf16 v[44:47], v[160:163], v[192:195], v[44:47]
	s_add_i32 s68, 0, 0x18000
	v_mfma_f32_16x16x32_bf16 v[36:39], v[152:155], v[200:203], v[36:39]
	v_mfma_f32_16x16x32_bf16 v[28:31], v[160:163], v[200:203], v[28:31]
	s_add_i32 s69, 0, 0x1c000
	v_mfma_f32_16x16x32_bf16 v[20:23], v[152:155], v[208:211], v[20:23]
	v_mfma_f32_16x16x32_bf16 v[12:15], v[160:163], v[208:211], v[12:15]
	s_add_u32 s24, s30, 0xc0000
	v_mfma_f32_16x16x32_bf16 v[60:63], v[156:159], v[188:191], v[60:63]
	v_mfma_f32_16x16x32_bf16 v[56:59], v[164:167], v[188:191], v[56:59]
	s_addc_u32 s25, s31, 0
	v_mfma_f32_16x16x32_bf16 v[52:55], v[156:159], v[196:199], v[52:55]
	v_mfma_f32_16x16x32_bf16 v[44:47], v[164:167], v[196:199], v[44:47]
	v_mfma_f32_16x16x32_bf16 v[36:39], v[156:159], v[204:207], v[36:39]
	v_mfma_f32_16x16x32_bf16 v[28:31], v[164:167], v[204:207], v[28:31]
	v_mfma_f32_16x16x32_bf16 v[20:23], v[156:159], v[212:215], v[20:23]
	v_mfma_f32_16x16x32_bf16 v[12:15], v[164:167], v[212:215], v[12:15]
	v_mfma_f32_16x16x32_bf16 v[48:51], v[168:171], v[184:187], v[48:51]
	v_mfma_f32_16x16x32_bf16 v[40:43], v[176:179], v[184:187], v[40:43]
	v_mfma_f32_16x16x32_bf16 v[32:35], v[168:171], v[192:195], v[32:35]
	v_mfma_f32_16x16x32_bf16 v[24:27], v[176:179], v[192:195], v[24:27]
	v_mfma_f32_16x16x32_bf16 v[16:19], v[168:171], v[200:203], v[16:19]
	v_mfma_f32_16x16x32_bf16 v[8:11], v[176:179], v[200:203], v[8:11]
	v_mfma_f32_16x16x32_bf16 v[4:7], v[168:171], v[208:211], v[4:7]
	v_mfma_f32_16x16x32_bf16 v[0:3], v[176:179], v[208:211], v[0:3]
	v_mfma_f32_16x16x32_bf16 v[48:51], v[172:175], v[188:191], v[48:51]
	v_mfma_f32_16x16x32_bf16 v[40:43], v[180:183], v[188:191], v[40:43]
	v_mfma_f32_16x16x32_bf16 v[32:35], v[172:175], v[196:199], v[32:35]
	v_mfma_f32_16x16x32_bf16 v[24:27], v[180:183], v[196:199], v[24:27]
	v_mfma_f32_16x16x32_bf16 v[16:19], v[172:175], v[204:207], v[16:19]
	v_mfma_f32_16x16x32_bf16 v[8:11], v[180:183], v[204:207], v[8:11]
	v_mfma_f32_16x16x32_bf16 v[4:7], v[172:175], v[212:215], v[4:7]
	v_mfma_f32_16x16x32_bf16 v[0:3], v[180:183], v[212:215], v[0:3]
	s_barrier
	ds_read_b128 v[184:187], v151 offset:32768
	ds_read_b128 v[188:191], v151 offset:33792
	ds_read_b128 v[192:195], v151 offset:34816
	ds_read_b128 v[196:199], v151 offset:35840
	ds_read_b128 v[200:203], v151 offset:36864
	ds_read_b128 v[204:207], v151 offset:37888
	ds_read_b128 v[208:211], v151 offset:38912
	ds_read_b128 v[212:215], v151 offset:39936
	v_add_u32_e32 v164, s68, v147
	v_add_u32_e32 v180, s69, v147
	ds_read_b128 v[152:155], v164
	ds_read_b128 v[156:159], v164 offset:1024
	ds_read_b128 v[160:163], v164 offset:2048
	ds_read_b128 v[164:167], v164 offset:3072
	ds_read_b128 v[168:171], v180
	ds_read_b128 v[172:175], v180 offset:1024
	ds_read_b128 v[176:179], v180 offset:2048
	ds_read_b128 v[180:183], v180 offset:3072
	s_mov_b32 m0, s48
	s_nop 0
	global_load_lds_dwordx4 v134, s[24:25]
	s_mov_b32 m0, s49
	s_nop 0
	global_load_lds_dwordx4 v130, s[24:25]
	s_waitcnt vmcnt(8)
	s_waitcnt lgkmcnt(0)
	s_barrier
	s_waitcnt lgkmcnt(0)
	v_mfma_f32_16x16x32_bf16 v[124:127], v[152:155], v[184:187], v[124:127]
	v_mfma_f32_16x16x32_bf16 v[120:123], v[160:163], v[184:187], v[120:123]
	v_mfma_f32_16x16x32_bf16 v[116:119], v[152:155], v[192:195], v[116:119]
	v_mfma_f32_16x16x32_bf16 v[108:111], v[160:163], v[192:195], v[108:111]
	s_add_i32 s24, s68, s40
	v_mfma_f32_16x16x32_bf16 v[100:103], v[152:155], v[200:203], v[100:103]
	v_mfma_f32_16x16x32_bf16 v[92:95], v[160:163], v[200:203], v[92:95]
	v_mfma_f32_16x16x32_bf16 v[84:87], v[152:155], v[208:211], v[84:87]
	v_mfma_f32_16x16x32_bf16 v[76:79], v[160:163], v[208:211], v[76:79]
	v_mfma_f32_16x16x32_bf16 v[124:127], v[156:159], v[188:191], v[124:127]
	v_mfma_f32_16x16x32_bf16 v[120:123], v[164:167], v[188:191], v[120:123]
	v_mfma_f32_16x16x32_bf16 v[116:119], v[156:159], v[196:199], v[116:119]
	v_mfma_f32_16x16x32_bf16 v[108:111], v[164:167], v[196:199], v[108:111]
	v_mfma_f32_16x16x32_bf16 v[100:103], v[156:159], v[204:207], v[100:103]
	v_mfma_f32_16x16x32_bf16 v[92:95], v[164:167], v[204:207], v[92:95]
	v_mfma_f32_16x16x32_bf16 v[84:87], v[156:159], v[212:215], v[84:87]
	v_mfma_f32_16x16x32_bf16 v[76:79], v[164:167], v[212:215], v[76:79]
	v_mfma_f32_16x16x32_bf16 v[112:115], v[168:171], v[184:187], v[112:115]
	v_mfma_f32_16x16x32_bf16 v[104:107], v[176:179], v[184:187], v[104:107]
	v_mfma_f32_16x16x32_bf16 v[96:99], v[168:171], v[192:195], v[96:99]
	v_mfma_f32_16x16x32_bf16 v[88:91], v[176:179], v[192:195], v[88:91]
	v_mfma_f32_16x16x32_bf16 v[80:83], v[168:171], v[200:203], v[80:83]
	v_mfma_f32_16x16x32_bf16 v[72:75], v[176:179], v[200:203], v[72:75]
	v_mfma_f32_16x16x32_bf16 v[68:71], v[168:171], v[208:211], v[68:71]
	v_mfma_f32_16x16x32_bf16 v[64:67], v[176:179], v[208:211], v[64:67]
	v_mfma_f32_16x16x32_bf16 v[112:115], v[172:175], v[188:191], v[112:115]
	v_mfma_f32_16x16x32_bf16 v[104:107], v[180:183], v[188:191], v[104:107]
	v_mfma_f32_16x16x32_bf16 v[96:99], v[172:175], v[196:199], v[96:99]
	v_mfma_f32_16x16x32_bf16 v[88:91], v[180:183], v[196:199], v[88:91]
	v_mfma_f32_16x16x32_bf16 v[80:83], v[172:175], v[204:207], v[80:83]
	v_mfma_f32_16x16x32_bf16 v[72:75], v[180:183], v[204:207], v[72:75]
	v_mfma_f32_16x16x32_bf16 v[68:71], v[172:175], v[212:215], v[68:71]
	v_mfma_f32_16x16x32_bf16 v[64:67], v[180:183], v[212:215], v[64:67]
	s_barrier
	ds_read_b128 v[184:187], v151 offset:49152
	ds_read_b128 v[188:191], v151 offset:50176
	ds_read_b128 v[192:195], v151 offset:51200
	ds_read_b128 v[196:199], v151 offset:52224
	ds_read_b128 v[200:203], v151 offset:53248
	ds_read_b128 v[204:207], v151 offset:54272
	ds_read_b128 v[208:211], v151 offset:55296
	ds_read_b128 v[212:215], v151 offset:56320
	s_mov_b32 m0, s24
	s_nop 0
	global_load_lds_dwordx4 v132, s[98:99]
	s_add_i32 m0, s24, 0x2000
	s_add_u32 s24, s28, 0x30080
	s_addc_u32 s25, s29, 0
	s_add_i32 s28, s69, s40
	global_load_lds_dwordx4 v128, s[98:99]
	s_mov_b32 m0, s28
	s_nop 0
	global_load_lds_dwordx4 v132, s[24:25]
	s_add_i32 m0, s28, 0x2000
	s_nop 0
	global_load_lds_dwordx4 v128, s[24:25]
	s_mov_b32 m0, s52
	s_nop 0
	global_load_lds_dwordx4 v134, s[100:101]
	s_mov_b32 m0, s53
	s_nop 0
	global_load_lds_dwordx4 v130, s[100:101]
	s_waitcnt vmcnt(8)
	s_waitcnt lgkmcnt(0)
	s_barrier
	s_waitcnt lgkmcnt(0)
	v_mfma_f32_16x16x32_bf16 v[60:63], v[152:155], v[184:187], v[60:63]
	v_mfma_f32_16x16x32_bf16 v[56:59], v[160:163], v[184:187], v[56:59]
	v_mfma_f32_16x16x32_bf16 v[52:55], v[152:155], v[192:195], v[52:55]
	v_mfma_f32_16x16x32_bf16 v[44:47], v[160:163], v[192:195], v[44:47]
	v_mfma_f32_16x16x32_bf16 v[36:39], v[152:155], v[200:203], v[36:39]
	v_mfma_f32_16x16x32_bf16 v[28:31], v[160:163], v[200:203], v[28:31]
	v_mfma_f32_16x16x32_bf16 v[20:23], v[152:155], v[208:211], v[20:23]
	v_mfma_f32_16x16x32_bf16 v[12:15], v[160:163], v[208:211], v[12:15]
	v_mfma_f32_16x16x32_bf16 v[60:63], v[156:159], v[188:191], v[60:63]
	v_mfma_f32_16x16x32_bf16 v[56:59], v[164:167], v[188:191], v[56:59]
	v_mfma_f32_16x16x32_bf16 v[52:55], v[156:159], v[196:199], v[52:55]
	v_mfma_f32_16x16x32_bf16 v[44:47], v[164:167], v[196:199], v[44:47]
	v_mfma_f32_16x16x32_bf16 v[36:39], v[156:159], v[204:207], v[36:39]
	v_mfma_f32_16x16x32_bf16 v[28:31], v[164:167], v[204:207], v[28:31]
	v_mfma_f32_16x16x32_bf16 v[20:23], v[156:159], v[212:215], v[20:23]
	v_mfma_f32_16x16x32_bf16 v[12:15], v[164:167], v[212:215], v[12:15]
	v_mfma_f32_16x16x32_bf16 v[48:51], v[168:171], v[184:187], v[48:51]
	v_mfma_f32_16x16x32_bf16 v[40:43], v[176:179], v[184:187], v[40:43]
	v_mfma_f32_16x16x32_bf16 v[32:35], v[168:171], v[192:195], v[32:35]
	v_mfma_f32_16x16x32_bf16 v[24:27], v[176:179], v[192:195], v[24:27]
	v_mfma_f32_16x16x32_bf16 v[16:19], v[168:171], v[200:203], v[16:19]
	v_mfma_f32_16x16x32_bf16 v[8:11], v[176:179], v[200:203], v[8:11]
	v_mfma_f32_16x16x32_bf16 v[4:7], v[168:171], v[208:211], v[4:7]
	v_mfma_f32_16x16x32_bf16 v[0:3], v[176:179], v[208:211], v[0:3]
	v_mfma_f32_16x16x32_bf16 v[48:51], v[172:175], v[188:191], v[48:51]
	v_mfma_f32_16x16x32_bf16 v[40:43], v[180:183], v[188:191], v[40:43]
	v_mfma_f32_16x16x32_bf16 v[32:35], v[172:175], v[196:199], v[32:35]
	v_mfma_f32_16x16x32_bf16 v[24:27], v[180:183], v[196:199], v[24:27]
	v_mfma_f32_16x16x32_bf16 v[16:19], v[172:175], v[204:207], v[16:19]
	v_mfma_f32_16x16x32_bf16 v[8:11], v[180:183], v[204:207], v[8:11]
	v_mfma_f32_16x16x32_bf16 v[4:7], v[172:175], v[212:215], v[4:7]
	v_mfma_f32_16x16x32_bf16 v[0:3], v[180:183], v[212:215], v[0:3]
	s_barrier
	s_add_i32 s67, s67, 2
	s_add_u32 s65, s65, 0x100
	s_addc_u32 s66, s66, 0
	s_cmp_gt_u32 s67, 9
	s_mov_b64 s[24:25], s[26:27]
	s_cbranch_scc0 .LBB0_254
	s_setprio 0
	s_and_b64 vcc, exec, s[12:13]
	s_cbranch_vccz .LBB0_257
	s_barrier

.Lsp_skip2:
.LBB0_281:
	ds_read_b128 v[144:147], v153
	ds_read_b128 v[156:159], v153 offset:1024
	ds_read_b128 v[160:163], v153 offset:2048
	ds_read_b128 v[164:167], v153 offset:3072
	ds_read_b128 v[168:171], v154
	ds_read_b128 v[172:175], v154 offset:1024
	ds_read_b128 v[176:179], v154 offset:2048
	ds_read_b128 v[180:183], v154 offset:3072
	ds_read_b128 v[184:187], v155
	ds_read_b128 v[188:191], v155 offset:1024
	ds_read_b128 v[192:195], v155 offset:2048
	ds_read_b128 v[196:199], v155 offset:3072
	ds_read_b128 v[200:203], v155 offset:4096
	ds_read_b128 v[204:207], v155 offset:5120
	ds_read_b128 v[208:211], v155 offset:6144
	ds_read_b128 v[212:215], v155 offset:7168
	s_add_u32 s34, s30, 0xfff80080
	s_addc_u32 s35, s31, -1
	s_cmp_eq_u32 s61, 28
	s_cselect_b32 s37, s23, s35
	s_cselect_b32 s36, s57, s34
	s_cselect_b32 s35, s21, s60
	s_cselect_b32 s34, s58, s59
	s_add_i32 m0, s29, 0xc000
	s_nop 0
	global_load_lds_dwordx4 v138, s[30:31]
	s_add_i32 m0, s29, 0xe000
	s_nop 0
	global_load_lds_dwordx4 v136, s[30:31]
	s_waitcnt vmcnt(8)
	s_waitcnt lgkmcnt(0)
	s_barrier
	s_waitcnt lgkmcnt(0)
	v_mfma_i32_16x16x64_i8 v[124:127], v[144:147], v[184:187], v[124:127]
	v_mfma_i32_16x16x64_i8 v[120:123], v[160:163], v[184:187], v[120:123]
	v_mfma_i32_16x16x64_i8 v[108:111], v[144:147], v[192:195], v[108:111]
	v_mfma_i32_16x16x64_i8 v[104:107], v[160:163], v[192:195], v[104:107]
	s_add_u32 s98, s34, s6
	s_addc_u32 s99, s35, s7
	s_add_i32 s62, s41, s40
	v_mfma_i32_16x16x64_i8 v[92:95], v[144:147], v[200:203], v[92:95]
	s_add_u32 s100, s36, s6
	s_addc_u32 s101, s37, s7
	v_mfma_i32_16x16x64_i8 v[88:91], v[160:163], v[200:203], v[88:91]
	v_mfma_i32_16x16x64_i8 v[76:79], v[144:147], v[208:211], v[76:79]
	v_mfma_i32_16x16x64_i8 v[72:75], v[160:163], v[208:211], v[72:75]
	v_mfma_i32_16x16x64_i8 v[124:127], v[156:159], v[188:191], v[124:127]
	v_mfma_i32_16x16x64_i8 v[120:123], v[164:167], v[188:191], v[120:123]
	s_add_i32 s64, s42, s40
	v_mfma_i32_16x16x64_i8 v[108:111], v[156:159], v[196:199], v[108:111]
	v_mfma_i32_16x16x64_i8 v[104:107], v[164:167], v[196:199], v[104:107]
	v_mfma_i32_16x16x64_i8 v[92:95], v[156:159], v[204:207], v[92:95]
	v_mfma_i32_16x16x64_i8 v[88:91], v[164:167], v[204:207], v[88:91]
	v_mfma_i32_16x16x64_i8 v[76:79], v[156:159], v[212:215], v[76:79]
	v_mfma_i32_16x16x64_i8 v[72:75], v[164:167], v[212:215], v[72:75]
	v_mfma_i32_16x16x64_i8 v[116:119], v[168:171], v[184:187], v[116:119]
	v_mfma_i32_16x16x64_i8 v[112:115], v[176:179], v[184:187], v[112:115]
	v_mfma_i32_16x16x64_i8 v[100:103], v[168:171], v[192:195], v[100:103]
	v_mfma_i32_16x16x64_i8 v[96:99], v[176:179], v[192:195], v[96:99]
	v_mfma_i32_16x16x64_i8 v[84:87], v[168:171], v[200:203], v[84:87]
	v_mfma_i32_16x16x64_i8 v[80:83], v[176:179], v[200:203], v[80:83]
	v_mfma_i32_16x16x64_i8 v[68:71], v[168:171], v[208:211], v[68:71]
	v_mfma_i32_16x16x64_i8 v[64:67], v[176:179], v[208:211], v[64:67]
	v_mfma_i32_16x16x64_i8 v[116:119], v[172:175], v[188:191], v[116:119]
	v_mfma_i32_16x16x64_i8 v[112:115], v[180:183], v[188:191], v[112:115]
	v_mfma_i32_16x16x64_i8 v[100:103], v[172:175], v[196:199], v[100:103]
	v_mfma_i32_16x16x64_i8 v[96:99], v[180:183], v[196:199], v[96:99]
	v_mfma_i32_16x16x64_i8 v[84:87], v[172:175], v[204:207], v[84:87]
	v_mfma_i32_16x16x64_i8 v[80:83], v[180:183], v[204:207], v[80:83]
	v_mfma_i32_16x16x64_i8 v[68:71], v[172:175], v[212:215], v[68:71]
	v_mfma_i32_16x16x64_i8 v[64:67], v[180:183], v[212:215], v[64:67]
	s_barrier
	ds_read_b128 v[184:187], v155 offset:16384
	ds_read_b128 v[188:191], v155 offset:17408
	ds_read_b128 v[192:195], v155 offset:18432
	ds_read_b128 v[196:199], v155 offset:19456
	ds_read_b128 v[200:203], v155 offset:20480
	ds_read_b128 v[204:207], v155 offset:21504
	ds_read_b128 v[208:211], v155 offset:22528
	ds_read_b128 v[212:215], v155 offset:23552
	s_mov_b32 m0, s62
	s_nop 0
	global_load_lds_dwordx4 v130, s[34:35]
	s_add_i32 m0, s62, 0x2000
	s_add_u32 s62, s34, 0x80000
	s_addc_u32 s63, s35, 0
	global_load_lds_dwordx4 v134, s[34:35]
	s_mov_b32 m0, s64
	s_nop 0
	global_load_lds_dwordx4 v130, s[62:63]
	s_add_i32 m0, s64, 0x2000
	s_nop 0
	global_load_lds_dwordx4 v134, s[62:63]
	s_mov_b32 m0, s29
	s_nop 0
	global_load_lds_dwordx4 v128, s[36:37]
	s_mov_b32 m0, s48
	s_nop 0
	global_load_lds_dwordx4 v132, s[36:37]
	s_waitcnt vmcnt(8)
	s_waitcnt lgkmcnt(0)
	s_barrier
	s_waitcnt lgkmcnt(0)
	v_mfma_i32_16x16x64_i8 v[60:63], v[144:147], v[184:187], v[60:63]
	v_mfma_i32_16x16x64_i8 v[56:59], v[160:163], v[184:187], v[56:59]
	v_mfma_i32_16x16x64_i8 v[44:47], v[144:147], v[192:195], v[44:47]
	v_mfma_i32_16x16x64_i8 v[40:43], v[160:163], v[192:195], v[40:43]
	s_add_i32 s62, 0, 0x18000
	v_mfma_i32_16x16x64_i8 v[28:31], v[144:147], v[200:203], v[28:31]
	v_mfma_i32_16x16x64_i8 v[24:27], v[160:163], v[200:203], v[24:27]
	s_add_i32 s63, 0, 0x1c000
	v_mfma_i32_16x16x64_i8 v[12:15], v[144:147], v[208:211], v[12:15]
	v_mfma_i32_16x16x64_i8 v[8:11], v[160:163], v[208:211], v[8:11]
	s_add_u32 s36, s36, 0x80000
	v_mfma_i32_16x16x64_i8 v[60:63], v[156:159], v[188:191], v[60:63]
	v_mfma_i32_16x16x64_i8 v[56:59], v[164:167], v[188:191], v[56:59]
	s_addc_u32 s37, s37, 0
	v_mfma_i32_16x16x64_i8 v[44:47], v[156:159], v[196:199], v[44:47]
	v_mfma_i32_16x16x64_i8 v[40:43], v[164:167], v[196:199], v[40:43]
	v_mfma_i32_16x16x64_i8 v[28:31], v[156:159], v[204:207], v[28:31]
	v_mfma_i32_16x16x64_i8 v[24:27], v[164:167], v[204:207], v[24:27]
	v_mfma_i32_16x16x64_i8 v[12:15], v[156:159], v[212:215], v[12:15]
	v_mfma_i32_16x16x64_i8 v[8:11], v[164:167], v[212:215], v[8:11]
	v_mfma_i32_16x16x64_i8 v[52:55], v[168:171], v[184:187], v[52:55]
	v_mfma_i32_16x16x64_i8 v[48:51], v[176:179], v[184:187], v[48:51]
	v_mfma_i32_16x16x64_i8 v[36:39], v[168:171], v[192:195], v[36:39]
	v_mfma_i32_16x16x64_i8 v[32:35], v[176:179], v[192:195], v[32:35]
	v_mfma_i32_16x16x64_i8 v[20:23], v[168:171], v[200:203], v[20:23]
	v_mfma_i32_16x16x64_i8 v[16:19], v[176:179], v[200:203], v[16:19]
	v_mfma_i32_16x16x64_i8 v[4:7], v[168:171], v[208:211], v[4:7]
	v_mfma_i32_16x16x64_i8 v[0:3], v[176:179], v[208:211], v[0:3]
	v_mfma_i32_16x16x64_i8 v[52:55], v[172:175], v[188:191], v[52:55]
	v_mfma_i32_16x16x64_i8 v[48:51], v[180:183], v[188:191], v[48:51]
	v_mfma_i32_16x16x64_i8 v[36:39], v[172:175], v[196:199], v[36:39]
	v_mfma_i32_16x16x64_i8 v[32:35], v[180:183], v[196:199], v[32:35]
	v_mfma_i32_16x16x64_i8 v[20:23], v[172:175], v[204:207], v[20:23]
	v_mfma_i32_16x16x64_i8 v[16:19], v[180:183], v[204:207], v[16:19]
	v_mfma_i32_16x16x64_i8 v[4:7], v[172:175], v[212:215], v[4:7]
	v_mfma_i32_16x16x64_i8 v[0:3], v[180:183], v[212:215], v[0:3]
	s_barrier
	ds_read_b128 v[184:187], v155 offset:32768
	ds_read_b128 v[188:191], v155 offset:33792
	ds_read_b128 v[192:195], v155 offset:34816
	ds_read_b128 v[196:199], v155 offset:35840
	ds_read_b128 v[200:203], v155 offset:36864
	ds_read_b128 v[204:207], v155 offset:37888
	ds_read_b128 v[208:211], v155 offset:38912
	ds_read_b128 v[212:215], v155 offset:39936
	v_add_u32_e32 v164, s62, v151
	v_add_u32_e32 v180, s63, v151
	ds_read_b128 v[144:147], v164
	ds_read_b128 v[156:159], v164 offset:1024
	ds_read_b128 v[160:163], v164 offset:2048
	ds_read_b128 v[164:167], v164 offset:3072
	ds_read_b128 v[168:171], v180
	ds_read_b128 v[172:175], v180 offset:1024
	ds_read_b128 v[176:179], v180 offset:2048
	ds_read_b128 v[180:183], v180 offset:3072
	s_mov_b32 m0, s49
	s_nop 0
	global_load_lds_dwordx4 v128, s[36:37]
	s_mov_b32 m0, s50
	s_nop 0
	global_load_lds_dwordx4 v132, s[36:37]
	s_waitcnt vmcnt(8)
	s_waitcnt lgkmcnt(0)
	s_barrier
	s_waitcnt lgkmcnt(0)
	v_mfma_i32_16x16x64_i8 v[124:127], v[144:147], v[184:187], v[124:127]
	v_mfma_i32_16x16x64_i8 v[120:123], v[160:163], v[184:187], v[120:123]
	v_mfma_i32_16x16x64_i8 v[108:111], v[144:147], v[192:195], v[108:111]
	v_mfma_i32_16x16x64_i8 v[104:107], v[160:163], v[192:195], v[104:107]
	s_add_i32 s36, s62, s40
	v_mfma_i32_16x16x64_i8 v[92:95], v[144:147], v[200:203], v[92:95]
	v_mfma_i32_16x16x64_i8 v[88:91], v[160:163], v[200:203], v[88:91]
	v_mfma_i32_16x16x64_i8 v[76:79], v[144:147], v[208:211], v[76:79]
	v_mfma_i32_16x16x64_i8 v[72:75], v[160:163], v[208:211], v[72:75]
	s_add_u32 s34, s34, 0x80080
	v_mfma_i32_16x16x64_i8 v[124:127], v[156:159], v[188:191], v[124:127]
	v_mfma_i32_16x16x64_i8 v[120:123], v[164:167], v[188:191], v[120:123]
	v_mfma_i32_16x16x64_i8 v[108:111], v[156:159], v[196:199], v[108:111]
	v_mfma_i32_16x16x64_i8 v[104:107], v[164:167], v[196:199], v[104:107]
	s_addc_u32 s35, s35, 0
	v_mfma_i32_16x16x64_i8 v[92:95], v[156:159], v[204:207], v[92:95]
	v_mfma_i32_16x16x64_i8 v[88:91], v[164:167], v[204:207], v[88:91]
	v_mfma_i32_16x16x64_i8 v[76:79], v[156:159], v[212:215], v[76:79]
	v_mfma_i32_16x16x64_i8 v[72:75], v[164:167], v[212:215], v[72:75]
	v_mfma_i32_16x16x64_i8 v[116:119], v[168:171], v[184:187], v[116:119]
	v_mfma_i32_16x16x64_i8 v[112:115], v[176:179], v[184:187], v[112:115]
	v_mfma_i32_16x16x64_i8 v[100:103], v[168:171], v[192:195], v[100:103]
	v_mfma_i32_16x16x64_i8 v[96:99], v[176:179], v[192:195], v[96:99]
	v_mfma_i32_16x16x64_i8 v[84:87], v[168:171], v[200:203], v[84:87]
	v_mfma_i32_16x16x64_i8 v[80:83], v[176:179], v[200:203], v[80:83]
	v_mfma_i32_16x16x64_i8 v[68:71], v[168:171], v[208:211], v[68:71]
	v_mfma_i32_16x16x64_i8 v[64:67], v[176:179], v[208:211], v[64:67]
	v_mfma_i32_16x16x64_i8 v[116:119], v[172:175], v[188:191], v[116:119]
	v_mfma_i32_16x16x64_i8 v[112:115], v[180:183], v[188:191], v[112:115]
	v_mfma_i32_16x16x64_i8 v[100:103], v[172:175], v[196:199], v[100:103]
	v_mfma_i32_16x16x64_i8 v[96:99], v[180:183], v[196:199], v[96:99]
	v_mfma_i32_16x16x64_i8 v[84:87], v[172:175], v[204:207], v[84:87]
	v_mfma_i32_16x16x64_i8 v[80:83], v[180:183], v[204:207], v[80:83]
	v_mfma_i32_16x16x64_i8 v[68:71], v[172:175], v[212:215], v[68:71]
	v_mfma_i32_16x16x64_i8 v[64:67], v[180:183], v[212:215], v[64:67]
	s_barrier
	ds_read_b128 v[184:187], v155 offset:49152
	ds_read_b128 v[188:191], v155 offset:50176
	ds_read_b128 v[192:195], v155 offset:51200
	ds_read_b128 v[196:199], v155 offset:52224
	ds_read_b128 v[200:203], v155 offset:53248
	ds_read_b128 v[204:207], v155 offset:54272
	ds_read_b128 v[208:211], v155 offset:55296
	ds_read_b128 v[212:215], v155 offset:56320
	s_mov_b32 m0, s36
	s_nop 0
	global_load_lds_dwordx4 v130, s[98:99]
	s_add_i32 m0, s36, 0x2000
	s_add_i32 s36, s63, s40
	global_load_lds_dwordx4 v134, s[98:99]
	s_mov_b32 m0, s36
	s_nop 0
	global_load_lds_dwordx4 v130, s[34:35]
	s_add_i32 m0, s36, 0x2000
	s_nop 0
	global_load_lds_dwordx4 v134, s[34:35]
	s_mov_b32 m0, s44
	s_nop 0
	global_load_lds_dwordx4 v128, s[100:101]
	s_mov_b32 m0, s52
	s_nop 0
	global_load_lds_dwordx4 v132, s[100:101]
	s_waitcnt vmcnt(8)
	s_waitcnt lgkmcnt(0)
	s_barrier
	s_waitcnt lgkmcnt(0)
	v_mfma_i32_16x16x64_i8 v[60:63], v[144:147], v[184:187], v[60:63]
	v_mfma_i32_16x16x64_i8 v[56:59], v[160:163], v[184:187], v[56:59]
	v_mfma_i32_16x16x64_i8 v[44:47], v[144:147], v[192:195], v[44:47]
	v_mfma_i32_16x16x64_i8 v[40:43], v[160:163], v[192:195], v[40:43]
	v_mfma_i32_16x16x64_i8 v[28:31], v[144:147], v[200:203], v[28:31]
	v_mfma_i32_16x16x64_i8 v[24:27], v[160:163], v[200:203], v[24:27]
	v_mfma_i32_16x16x64_i8 v[12:15], v[144:147], v[208:211], v[12:15]
	v_mfma_i32_16x16x64_i8 v[8:11], v[160:163], v[208:211], v[8:11]
	v_mfma_i32_16x16x64_i8 v[60:63], v[156:159], v[188:191], v[60:63]
	v_mfma_i32_16x16x64_i8 v[56:59], v[164:167], v[188:191], v[56:59]
	v_mfma_i32_16x16x64_i8 v[44:47], v[156:159], v[196:199], v[44:47]
	v_mfma_i32_16x16x64_i8 v[40:43], v[164:167], v[196:199], v[40:43]
	v_mfma_i32_16x16x64_i8 v[28:31], v[156:159], v[204:207], v[28:31]
	v_mfma_i32_16x16x64_i8 v[24:27], v[164:167], v[204:207], v[24:27]
	v_mfma_i32_16x16x64_i8 v[12:15], v[156:159], v[212:215], v[12:15]
	v_mfma_i32_16x16x64_i8 v[8:11], v[164:167], v[212:215], v[8:11]
	v_mfma_i32_16x16x64_i8 v[52:55], v[168:171], v[184:187], v[52:55]
	v_mfma_i32_16x16x64_i8 v[48:51], v[176:179], v[184:187], v[48:51]
	v_mfma_i32_16x16x64_i8 v[36:39], v[168:171], v[192:195], v[36:39]
	v_mfma_i32_16x16x64_i8 v[32:35], v[176:179], v[192:195], v[32:35]
	v_mfma_i32_16x16x64_i8 v[20:23], v[168:171], v[200:203], v[20:23]
	v_mfma_i32_16x16x64_i8 v[16:19], v[176:179], v[200:203], v[16:19]
	v_mfma_i32_16x16x64_i8 v[4:7], v[168:171], v[208:211], v[4:7]
	v_mfma_i32_16x16x64_i8 v[0:3], v[176:179], v[208:211], v[0:3]
	v_mfma_i32_16x16x64_i8 v[52:55], v[172:175], v[188:191], v[52:55]
	v_mfma_i32_16x16x64_i8 v[48:51], v[180:183], v[188:191], v[48:51]
	v_mfma_i32_16x16x64_i8 v[36:39], v[172:175], v[196:199], v[36:39]
	v_mfma_i32_16x16x64_i8 v[32:35], v[180:183], v[196:199], v[32:35]
	v_mfma_i32_16x16x64_i8 v[20:23], v[172:175], v[204:207], v[20:23]
	v_mfma_i32_16x16x64_i8 v[16:19], v[180:183], v[204:207], v[16:19]
	v_mfma_i32_16x16x64_i8 v[4:7], v[172:175], v[212:215], v[4:7]
	v_mfma_i32_16x16x64_i8 v[0:3], v[180:183], v[212:215], v[0:3]
	s_barrier
	s_add_i32 s61, s61, 2
	s_add_u32 s59, s59, 0x100
	s_addc_u32 s60, s60, 0
	s_add_u32 s30, s30, 0x100
	s_addc_u32 s31, s31, 0
	s_cmp_gt_u32 s61, 29
	s_cbranch_scc0 .LBB0_281
	s_setprio 0
	s_and_b64 vcc, exec, s[8:9]
	s_cbranch_vccz .LBB0_284
	s_barrier

.Lsp_skip3:
.LBB0_451:
	ds_read_b128 v[112:115], v193
	ds_read_b128 v[124:127], v193 offset:1024
	ds_read_b128 v[136:139], v193 offset:2048
	ds_read_b128 v[140:143], v193 offset:3072
	ds_read_b128 v[144:147], v194
	ds_read_b128 v[148:151], v194 offset:1024
	ds_read_b128 v[168:171], v194 offset:2048
	ds_read_b128 v[172:175], v194 offset:3072
	ds_read_b128 v[176:179], v195
	ds_read_b128 v[180:183], v195 offset:1024
	ds_read_b128 v[184:187], v195 offset:2048
	ds_read_b128 v[200:203], v195 offset:3072
	ds_read_b128 v[204:207], v195 offset:4096
	ds_read_b128 v[208:211], v195 offset:5120
	ds_read_b128 v[212:215], v195 offset:6144
	ds_read_b128 v[216:219], v195 offset:7168
	s_add_u32 s34, s30, 0xfff00080
	s_addc_u32 s35, s31, -1
	s_cmp_eq_u32 s58, 60
	s_cselect_b32 s37, s21, s35
	s_cselect_b32 s36, s27, s34
	s_cselect_b32 s35, s19, s57
	s_cselect_b32 s34, s55, s56
	s_add_i32 m0, s29, 0xc000
	s_nop 0
	global_load_lds_dwordx4 v162, s[30:31]
	s_add_i32 m0, s29, 0xe000
	s_nop 0
	global_load_lds_dwordx4 v160, s[30:31]
	s_waitcnt vmcnt(8)
	s_waitcnt lgkmcnt(0)
	s_barrier
	s_waitcnt lgkmcnt(0)
	v_mfma_f32_16x16x32_bf16 v[132:135], v[112:115], v[176:179], v[132:135]
	v_mfma_f32_16x16x32_bf16 v[128:131], v[136:139], v[176:179], v[128:131]
	v_mfma_f32_16x16x32_bf16 v[108:111], v[112:115], v[184:187], v[108:111]
	v_mfma_f32_16x16x32_bf16 v[104:107], v[136:139], v[184:187], v[104:107]
	s_add_u32 s98, s34, s14
	s_addc_u32 s99, s35, s15
	s_add_i32 s59, s50, s41
	v_mfma_f32_16x16x32_bf16 v[92:95], v[112:115], v[204:207], v[92:95]
	s_add_u32 s100, s36, s14
	s_addc_u32 s101, s37, s15
	v_mfma_f32_16x16x32_bf16 v[88:91], v[136:139], v[204:207], v[88:91]
	v_mfma_f32_16x16x32_bf16 v[76:79], v[112:115], v[212:215], v[76:79]
	v_mfma_f32_16x16x32_bf16 v[72:75], v[136:139], v[212:215], v[72:75]
	s_add_u32 s60, s34, 0x100000
	v_mfma_f32_16x16x32_bf16 v[132:135], v[124:127], v[180:183], v[132:135]
	v_mfma_f32_16x16x32_bf16 v[128:131], v[140:143], v[180:183], v[128:131]
	v_mfma_f32_16x16x32_bf16 v[108:111], v[124:127], v[200:203], v[108:111]
	v_mfma_f32_16x16x32_bf16 v[104:107], v[140:143], v[200:203], v[104:107]
	s_addc_u32 s61, s35, 0
	v_mfma_f32_16x16x32_bf16 v[92:95], v[124:127], v[208:211], v[92:95]
	v_mfma_f32_16x16x32_bf16 v[88:91], v[140:143], v[208:211], v[88:91]
	v_mfma_f32_16x16x32_bf16 v[76:79], v[124:127], v[216:219], v[76:79]
	v_mfma_f32_16x16x32_bf16 v[72:75], v[140:143], v[216:219], v[72:75]
	v_mfma_f32_16x16x32_bf16 v[120:123], v[144:147], v[176:179], v[120:123]
	v_mfma_f32_16x16x32_bf16 v[116:119], v[168:171], v[176:179], v[116:119]
	v_mfma_f32_16x16x32_bf16 v[100:103], v[144:147], v[184:187], v[100:103]
	v_mfma_f32_16x16x32_bf16 v[96:99], v[168:171], v[184:187], v[96:99]
	v_mfma_f32_16x16x32_bf16 v[84:87], v[144:147], v[204:207], v[84:87]
	v_mfma_f32_16x16x32_bf16 v[80:83], v[168:171], v[204:207], v[80:83]
	v_mfma_f32_16x16x32_bf16 v[68:71], v[144:147], v[212:215], v[68:71]
	v_mfma_f32_16x16x32_bf16 v[64:67], v[168:171], v[212:215], v[64:67]
	v_mfma_f32_16x16x32_bf16 v[120:123], v[148:151], v[180:183], v[120:123]
	v_mfma_f32_16x16x32_bf16 v[116:119], v[172:175], v[180:183], v[116:119]
	v_mfma_f32_16x16x32_bf16 v[100:103], v[148:151], v[200:203], v[100:103]
	v_mfma_f32_16x16x32_bf16 v[96:99], v[172:175], v[200:203], v[96:99]
	v_mfma_f32_16x16x32_bf16 v[84:87], v[148:151], v[208:211], v[84:87]
	v_mfma_f32_16x16x32_bf16 v[80:83], v[172:175], v[208:211], v[80:83]
	v_mfma_f32_16x16x32_bf16 v[68:71], v[148:151], v[216:219], v[68:71]
	v_mfma_f32_16x16x32_bf16 v[64:67], v[172:175], v[216:219], v[64:67]
	s_barrier
	ds_read_b128 v[176:179], v195 offset:16384
	ds_read_b128 v[180:183], v195 offset:17408
	ds_read_b128 v[184:187], v195 offset:18432
	ds_read_b128 v[200:203], v195 offset:19456
	ds_read_b128 v[204:207], v195 offset:20480
	ds_read_b128 v[208:211], v195 offset:21504
	ds_read_b128 v[212:215], v195 offset:22528
	ds_read_b128 v[216:219], v195 offset:23552
	s_mov_b32 m0, s59
	s_nop 0
	global_load_lds_dwordx4 v154, s[34:35]
	s_add_i32 m0, s59, 0x2000
	s_add_i32 s59, s51, s41
	global_load_lds_dwordx4 v158, s[34:35]
	s_mov_b32 m0, s59
	s_nop 0
	global_load_lds_dwordx4 v154, s[60:61]
	s_add_i32 m0, s59, 0x2000
	s_nop 0
	global_load_lds_dwordx4 v158, s[60:61]
	s_mov_b32 m0, s29
	s_nop 0
	global_load_lds_dwordx4 v152, s[36:37]
	s_mov_b32 m0, s42
	s_nop 0
	global_load_lds_dwordx4 v156, s[36:37]
	s_waitcnt vmcnt(8)
	s_waitcnt lgkmcnt(0)
	s_barrier
	s_waitcnt lgkmcnt(0)
	v_mfma_f32_16x16x32_bf16 v[60:63], v[112:115], v[176:179], v[60:63]
	v_mfma_f32_16x16x32_bf16 v[56:59], v[136:139], v[176:179], v[56:59]
	v_mfma_f32_16x16x32_bf16 v[44:47], v[112:115], v[184:187], v[44:47]
	v_mfma_f32_16x16x32_bf16 v[40:43], v[136:139], v[184:187], v[40:43]
	s_add_i32 s59, 0, 0x18000
	v_mfma_f32_16x16x32_bf16 v[28:31], v[112:115], v[204:207], v[28:31]
	v_mfma_f32_16x16x32_bf16 v[24:27], v[136:139], v[204:207], v[24:27]
	s_add_i32 s60, 0, 0x1c000
	v_mfma_f32_16x16x32_bf16 v[12:15], v[112:115], v[212:215], v[12:15]
	v_mfma_f32_16x16x32_bf16 v[8:11], v[136:139], v[212:215], v[8:11]
	s_add_u32 s36, s36, 0x100000
	v_mfma_f32_16x16x32_bf16 v[60:63], v[124:127], v[180:183], v[60:63]
	v_mfma_f32_16x16x32_bf16 v[56:59], v[140:143], v[180:183], v[56:59]
	s_addc_u32 s37, s37, 0
	v_mfma_f32_16x16x32_bf16 v[44:47], v[124:127], v[200:203], v[44:47]
	v_mfma_f32_16x16x32_bf16 v[40:43], v[140:143], v[200:203], v[40:43]
	v_mfma_f32_16x16x32_bf16 v[28:31], v[124:127], v[208:211], v[28:31]
	v_mfma_f32_16x16x32_bf16 v[24:27], v[140:143], v[208:211], v[24:27]
	v_mfma_f32_16x16x32_bf16 v[12:15], v[124:127], v[216:219], v[12:15]
	v_mfma_f32_16x16x32_bf16 v[8:11], v[140:143], v[216:219], v[8:11]
	v_mfma_f32_16x16x32_bf16 v[52:55], v[144:147], v[176:179], v[52:55]
	v_mfma_f32_16x16x32_bf16 v[48:51], v[168:171], v[176:179], v[48:51]
	v_mfma_f32_16x16x32_bf16 v[36:39], v[144:147], v[184:187], v[36:39]
	v_mfma_f32_16x16x32_bf16 v[32:35], v[168:171], v[184:187], v[32:35]
	v_mfma_f32_16x16x32_bf16 v[20:23], v[144:147], v[204:207], v[20:23]
	v_mfma_f32_16x16x32_bf16 v[16:19], v[168:171], v[204:207], v[16:19]
	v_mfma_f32_16x16x32_bf16 v[4:7], v[144:147], v[212:215], v[4:7]
	v_mfma_f32_16x16x32_bf16 v[0:3], v[168:171], v[212:215], v[0:3]
	v_mfma_f32_16x16x32_bf16 v[52:55], v[148:151], v[180:183], v[52:55]
	v_mfma_f32_16x16x32_bf16 v[48:51], v[172:175], v[180:183], v[48:51]
	v_mfma_f32_16x16x32_bf16 v[36:39], v[148:151], v[200:203], v[36:39]
	v_mfma_f32_16x16x32_bf16 v[32:35], v[172:175], v[200:203], v[32:35]
	v_mfma_f32_16x16x32_bf16 v[20:23], v[148:151], v[208:211], v[20:23]
	v_mfma_f32_16x16x32_bf16 v[16:19], v[172:175], v[208:211], v[16:19]
	v_mfma_f32_16x16x32_bf16 v[4:7], v[148:151], v[216:219], v[4:7]
	v_mfma_f32_16x16x32_bf16 v[0:3], v[172:175], v[216:219], v[0:3]
	s_barrier
	ds_read_b128 v[176:179], v195 offset:32768
	ds_read_b128 v[180:183], v195 offset:33792
	ds_read_b128 v[184:187], v195 offset:34816
	ds_read_b128 v[200:203], v195 offset:35840
	ds_read_b128 v[204:207], v195 offset:36864
	ds_read_b128 v[208:211], v195 offset:37888
	ds_read_b128 v[212:215], v195 offset:38912
	ds_read_b128 v[216:219], v195 offset:39936
	v_add_u32_e32 v140, s59, v191
	v_add_u32_e32 v172, s60, v191
	ds_read_b128 v[112:115], v140
	ds_read_b128 v[124:127], v140 offset:1024
	ds_read_b128 v[136:139], v140 offset:2048
	ds_read_b128 v[140:143], v140 offset:3072
	ds_read_b128 v[144:147], v172
	ds_read_b128 v[148:151], v172 offset:1024
	ds_read_b128 v[168:171], v172 offset:2048
	ds_read_b128 v[172:175], v172 offset:3072
	s_mov_b32 m0, s43
	s_nop 0
	global_load_lds_dwordx4 v152, s[36:37]
	s_mov_b32 m0, s44
	s_nop 0
	global_load_lds_dwordx4 v156, s[36:37]
	s_waitcnt vmcnt(8)
	s_waitcnt lgkmcnt(0)
	s_barrier
	s_waitcnt lgkmcnt(0)
	v_mfma_f32_16x16x32_bf16 v[132:135], v[112:115], v[176:179], v[132:135]
	v_mfma_f32_16x16x32_bf16 v[128:131], v[136:139], v[176:179], v[128:131]
	v_mfma_f32_16x16x32_bf16 v[108:111], v[112:115], v[184:187], v[108:111]
	v_mfma_f32_16x16x32_bf16 v[104:107], v[136:139], v[184:187], v[104:107]
	s_add_i32 s36, s59, s41
	v_mfma_f32_16x16x32_bf16 v[92:95], v[112:115], v[204:207], v[92:95]
	v_mfma_f32_16x16x32_bf16 v[88:91], v[136:139], v[204:207], v[88:91]
	v_mfma_f32_16x16x32_bf16 v[76:79], v[112:115], v[212:215], v[76:79]
	v_mfma_f32_16x16x32_bf16 v[72:75], v[136:139], v[212:215], v[72:75]
	s_add_u32 s34, s34, 0x100080
	v_mfma_f32_16x16x32_bf16 v[132:135], v[124:127], v[180:183], v[132:135]
	v_mfma_f32_16x16x32_bf16 v[128:131], v[140:143], v[180:183], v[128:131]
	v_mfma_f32_16x16x32_bf16 v[108:111], v[124:127], v[200:203], v[108:111]
	v_mfma_f32_16x16x32_bf16 v[104:107], v[140:143], v[200:203], v[104:107]
	s_addc_u32 s35, s35, 0
	v_mfma_f32_16x16x32_bf16 v[92:95], v[124:127], v[208:211], v[92:95]
	v_mfma_f32_16x16x32_bf16 v[88:91], v[140:143], v[208:211], v[88:91]
	v_mfma_f32_16x16x32_bf16 v[76:79], v[124:127], v[216:219], v[76:79]
	v_mfma_f32_16x16x32_bf16 v[72:75], v[140:143], v[216:219], v[72:75]
	v_mfma_f32_16x16x32_bf16 v[120:123], v[144:147], v[176:179], v[120:123]
	v_mfma_f32_16x16x32_bf16 v[116:119], v[168:171], v[176:179], v[116:119]
	v_mfma_f32_16x16x32_bf16 v[100:103], v[144:147], v[184:187], v[100:103]
	v_mfma_f32_16x16x32_bf16 v[96:99], v[168:171], v[184:187], v[96:99]
	v_mfma_f32_16x16x32_bf16 v[84:87], v[144:147], v[204:207], v[84:87]
	v_mfma_f32_16x16x32_bf16 v[80:83], v[168:171], v[204:207], v[80:83]
	v_mfma_f32_16x16x32_bf16 v[68:71], v[144:147], v[212:215], v[68:71]
	v_mfma_f32_16x16x32_bf16 v[64:67], v[168:171], v[212:215], v[64:67]
	v_mfma_f32_16x16x32_bf16 v[120:123], v[148:151], v[180:183], v[120:123]
	v_mfma_f32_16x16x32_bf16 v[116:119], v[172:175], v[180:183], v[116:119]
	v_mfma_f32_16x16x32_bf16 v[100:103], v[148:151], v[200:203], v[100:103]
	v_mfma_f32_16x16x32_bf16 v[96:99], v[172:175], v[200:203], v[96:99]
	v_mfma_f32_16x16x32_bf16 v[84:87], v[148:151], v[208:211], v[84:87]
	v_mfma_f32_16x16x32_bf16 v[80:83], v[172:175], v[208:211], v[80:83]
	v_mfma_f32_16x16x32_bf16 v[68:71], v[148:151], v[216:219], v[68:71]
	v_mfma_f32_16x16x32_bf16 v[64:67], v[172:175], v[216:219], v[64:67]
	s_barrier
	ds_read_b128 v[176:179], v195 offset:49152
	ds_read_b128 v[180:183], v195 offset:50176
	ds_read_b128 v[184:187], v195 offset:51200
	ds_read_b128 v[200:203], v195 offset:52224
	ds_read_b128 v[204:207], v195 offset:53248
	ds_read_b128 v[208:211], v195 offset:54272
	ds_read_b128 v[212:215], v195 offset:55296
	ds_read_b128 v[216:219], v195 offset:56320
	s_mov_b32 m0, s36
	s_nop 0
	global_load_lds_dwordx4 v154, s[98:99]
	s_add_i32 m0, s36, 0x2000
	s_add_i32 s36, s60, s41
	global_load_lds_dwordx4 v158, s[98:99]
	s_mov_b32 m0, s36
	s_nop 0
	global_load_lds_dwordx4 v154, s[34:35]
	s_add_i32 m0, s36, 0x2000
	s_nop 0
	global_load_lds_dwordx4 v158, s[34:35]
	s_mov_b32 m0, s46
	s_nop 0
	global_load_lds_dwordx4 v152, s[100:101]
	s_mov_b32 m0, s47
	s_nop 0
	global_load_lds_dwordx4 v156, s[100:101]
	s_waitcnt vmcnt(8)
	s_waitcnt lgkmcnt(0)
	s_barrier
	s_waitcnt lgkmcnt(0)
	v_mfma_f32_16x16x32_bf16 v[60:63], v[112:115], v[176:179], v[60:63]
	v_mfma_f32_16x16x32_bf16 v[56:59], v[136:139], v[176:179], v[56:59]
	v_mfma_f32_16x16x32_bf16 v[44:47], v[112:115], v[184:187], v[44:47]
	v_mfma_f32_16x16x32_bf16 v[40:43], v[136:139], v[184:187], v[40:43]
	v_mfma_f32_16x16x32_bf16 v[28:31], v[112:115], v[204:207], v[28:31]
	v_mfma_f32_16x16x32_bf16 v[24:27], v[136:139], v[204:207], v[24:27]
	v_mfma_f32_16x16x32_bf16 v[12:15], v[112:115], v[212:215], v[12:15]
	v_mfma_f32_16x16x32_bf16 v[8:11], v[136:139], v[212:215], v[8:11]
	v_mfma_f32_16x16x32_bf16 v[60:63], v[124:127], v[180:183], v[60:63]
	v_mfma_f32_16x16x32_bf16 v[56:59], v[140:143], v[180:183], v[56:59]
	v_mfma_f32_16x16x32_bf16 v[44:47], v[124:127], v[200:203], v[44:47]
	v_mfma_f32_16x16x32_bf16 v[40:43], v[140:143], v[200:203], v[40:43]
	v_mfma_f32_16x16x32_bf16 v[28:31], v[124:127], v[208:211], v[28:31]
	v_mfma_f32_16x16x32_bf16 v[24:27], v[140:143], v[208:211], v[24:27]
	v_mfma_f32_16x16x32_bf16 v[12:15], v[124:127], v[216:219], v[12:15]
	v_mfma_f32_16x16x32_bf16 v[8:11], v[140:143], v[216:219], v[8:11]
	v_mfma_f32_16x16x32_bf16 v[52:55], v[144:147], v[176:179], v[52:55]
	v_mfma_f32_16x16x32_bf16 v[48:51], v[168:171], v[176:179], v[48:51]
	v_mfma_f32_16x16x32_bf16 v[36:39], v[144:147], v[184:187], v[36:39]
	v_mfma_f32_16x16x32_bf16 v[32:35], v[168:171], v[184:187], v[32:35]
	v_mfma_f32_16x16x32_bf16 v[20:23], v[144:147], v[204:207], v[20:23]
	v_mfma_f32_16x16x32_bf16 v[16:19], v[168:171], v[204:207], v[16:19]
	v_mfma_f32_16x16x32_bf16 v[4:7], v[144:147], v[212:215], v[4:7]
	v_mfma_f32_16x16x32_bf16 v[0:3], v[168:171], v[212:215], v[0:3]
	v_mfma_f32_16x16x32_bf16 v[52:55], v[148:151], v[180:183], v[52:55]
	v_mfma_f32_16x16x32_bf16 v[48:51], v[172:175], v[180:183], v[48:51]
	v_mfma_f32_16x16x32_bf16 v[36:39], v[148:151], v[200:203], v[36:39]
	v_mfma_f32_16x16x32_bf16 v[32:35], v[172:175], v[200:203], v[32:35]
	v_mfma_f32_16x16x32_bf16 v[20:23], v[148:151], v[208:211], v[20:23]
	v_mfma_f32_16x16x32_bf16 v[16:19], v[172:175], v[208:211], v[16:19]
	v_mfma_f32_16x16x32_bf16 v[4:7], v[148:151], v[216:219], v[4:7]
	v_mfma_f32_16x16x32_bf16 v[0:3], v[172:175], v[216:219], v[0:3]
	s_barrier
	s_add_i32 s58, s58, 2
	s_add_u32 s56, s56, 0x100
	s_addc_u32 s57, s57, 0
	s_add_u32 s30, s30, 0x100
	s_addc_u32 s31, s31, 0
	s_cmp_gt_u32 s58, 61
	s_cbranch_scc0 .LBB0_451
	s_setprio 0
	s_and_b64 vcc, exec, s[16:17]
	s_cbranch_vccz .LBB0_454
	s_barrier

.Lsp_skip4:
.LBB0_550:
	ds_read_b128 v[144:147], v161
	ds_read_b128 v[148:151], v161 offset:1024
	ds_read_b128 v[170:173], v161 offset:2048
	ds_read_b128 v[174:177], v161 offset:3072
	ds_read_b128 v[178:181], v163
	ds_read_b128 v[182:185], v163 offset:1024
	ds_read_b128 v[186:189], v163 offset:2048
	ds_read_b128 v[190:193], v163 offset:3072
	ds_read_b128 v[194:197], v166
	ds_read_b128 v[198:201], v166 offset:1024
	ds_read_b128 v[202:205], v166 offset:2048
	ds_read_b128 v[206:209], v166 offset:3072
	ds_read_b128 v[210:213], v166 offset:4096
	ds_read_b128 v[214:217], v166 offset:5120
	ds_read_b128 v[218:221], v166 offset:6144
	ds_read_b128 v[222:225], v166 offset:7168
	s_add_u32 s6, s4, 0xfff80080
	s_addc_u32 s7, s5, -1
	s_cmp_eq_u32 s64, 28
	s_cselect_b32 s39, s1, s7
	s_cselect_b32 s38, s31, s6
	s_cselect_b32 s7, s29, s63
	s_cselect_b32 s6, s61, s62
	s_add_i32 m0, s45, 0xc000
	s_nop 0
	global_load_lds_dwordx4 v138, s[4:5]
	s_add_i32 m0, s45, 0xe000
	s_nop 0
	global_load_lds_dwordx4 v136, s[4:5]
	s_waitcnt vmcnt(8)
	s_waitcnt lgkmcnt(0)
	s_barrier
	s_waitcnt lgkmcnt(0)
	v_mfma_i32_16x16x64_i8 v[124:127], v[144:147], v[194:197], v[124:127]
	v_mfma_i32_16x16x64_i8 v[120:123], v[170:173], v[194:197], v[120:123]
	v_mfma_i32_16x16x64_i8 v[108:111], v[144:147], v[202:205], v[108:111]
	v_mfma_i32_16x16x64_i8 v[104:107], v[170:173], v[202:205], v[104:107]
	s_add_u32 s98, s6, s16
	s_addc_u32 s99, s7, s17
	s_add_i32 s65, s53, s44
	v_mfma_i32_16x16x64_i8 v[92:95], v[144:147], v[210:213], v[92:95]
	s_add_u32 s100, s38, s16
	s_addc_u32 s101, s39, s17
	v_mfma_i32_16x16x64_i8 v[88:91], v[170:173], v[210:213], v[88:91]
	v_mfma_i32_16x16x64_i8 v[76:79], v[144:147], v[218:221], v[76:79]
	v_mfma_i32_16x16x64_i8 v[72:75], v[170:173], v[218:221], v[72:75]
	s_add_u32 s66, s6, 0x80000
	v_mfma_i32_16x16x64_i8 v[124:127], v[148:151], v[198:201], v[124:127]
	v_mfma_i32_16x16x64_i8 v[120:123], v[174:177], v[198:201], v[120:123]
	v_mfma_i32_16x16x64_i8 v[108:111], v[148:151], v[206:209], v[108:111]
	v_mfma_i32_16x16x64_i8 v[104:107], v[174:177], v[206:209], v[104:107]
	s_addc_u32 s67, s7, 0
	v_mfma_i32_16x16x64_i8 v[92:95], v[148:151], v[214:217], v[92:95]
	v_mfma_i32_16x16x64_i8 v[88:91], v[174:177], v[214:217], v[88:91]
	v_mfma_i32_16x16x64_i8 v[76:79], v[148:151], v[222:225], v[76:79]
	v_mfma_i32_16x16x64_i8 v[72:75], v[174:177], v[222:225], v[72:75]
	v_mfma_i32_16x16x64_i8 v[116:119], v[178:181], v[194:197], v[116:119]
	v_mfma_i32_16x16x64_i8 v[112:115], v[186:189], v[194:197], v[112:115]
	v_mfma_i32_16x16x64_i8 v[100:103], v[178:181], v[202:205], v[100:103]
	v_mfma_i32_16x16x64_i8 v[96:99], v[186:189], v[202:205], v[96:99]
	v_mfma_i32_16x16x64_i8 v[84:87], v[178:181], v[210:213], v[84:87]
	v_mfma_i32_16x16x64_i8 v[80:83], v[186:189], v[210:213], v[80:83]
	v_mfma_i32_16x16x64_i8 v[68:71], v[178:181], v[218:221], v[68:71]
	v_mfma_i32_16x16x64_i8 v[64:67], v[186:189], v[218:221], v[64:67]
	v_mfma_i32_16x16x64_i8 v[116:119], v[182:185], v[198:201], v[116:119]
	v_mfma_i32_16x16x64_i8 v[112:115], v[190:193], v[198:201], v[112:115]
	v_mfma_i32_16x16x64_i8 v[100:103], v[182:185], v[206:209], v[100:103]
	v_mfma_i32_16x16x64_i8 v[96:99], v[190:193], v[206:209], v[96:99]
	v_mfma_i32_16x16x64_i8 v[84:87], v[182:185], v[214:217], v[84:87]
	v_mfma_i32_16x16x64_i8 v[80:83], v[190:193], v[214:217], v[80:83]
	v_mfma_i32_16x16x64_i8 v[68:71], v[182:185], v[222:225], v[68:71]
	v_mfma_i32_16x16x64_i8 v[64:67], v[190:193], v[222:225], v[64:67]
	s_barrier
	ds_read_b128 v[194:197], v166 offset:16384
	ds_read_b128 v[198:201], v166 offset:17408
	ds_read_b128 v[202:205], v166 offset:18432
	ds_read_b128 v[206:209], v166 offset:19456
	ds_read_b128 v[210:213], v166 offset:20480
	ds_read_b128 v[214:217], v166 offset:21504
	ds_read_b128 v[218:221], v166 offset:22528
	ds_read_b128 v[222:225], v166 offset:23552
	s_mov_b32 m0, s65
	s_nop 0
	global_load_lds_dwordx4 v130, s[6:7]
	s_add_i32 m0, s65, 0x2000
	s_add_i32 s65, s54, s44
	global_load_lds_dwordx4 v134, s[6:7]
	s_mov_b32 m0, s65
	s_nop 0
	global_load_lds_dwordx4 v130, s[66:67]
	s_add_i32 m0, s65, 0x2000
	s_nop 0
	global_load_lds_dwordx4 v134, s[66:67]
	s_mov_b32 m0, s45
	s_nop 0
	global_load_lds_dwordx4 v128, s[38:39]
	s_mov_b32 m0, s46
	s_nop 0
	global_load_lds_dwordx4 v132, s[38:39]
	s_waitcnt vmcnt(8)
	s_waitcnt lgkmcnt(0)
	s_barrier
	s_waitcnt lgkmcnt(0)
	v_mfma_i32_16x16x64_i8 v[60:63], v[144:147], v[194:197], v[60:63]
	v_mfma_i32_16x16x64_i8 v[56:59], v[170:173], v[194:197], v[56:59]
	v_mfma_i32_16x16x64_i8 v[44:47], v[144:147], v[202:205], v[44:47]
	v_mfma_i32_16x16x64_i8 v[40:43], v[170:173], v[202:205], v[40:43]
	s_add_i32 s65, 0, 0x18000
	v_mfma_i32_16x16x64_i8 v[28:31], v[144:147], v[210:213], v[28:31]
	v_mfma_i32_16x16x64_i8 v[24:27], v[170:173], v[210:213], v[24:27]
	v_add_u32_e32 v154, s65, v157
	v_mfma_i32_16x16x64_i8 v[12:15], v[144:147], v[218:221], v[12:15]
	v_mfma_i32_16x16x64_i8 v[8:11], v[170:173], v[218:221], v[8:11]
	s_add_i32 s66, 0, 0x1c000
	v_mfma_i32_16x16x64_i8 v[60:63], v[148:151], v[198:201], v[60:63]
	v_mfma_i32_16x16x64_i8 v[56:59], v[174:177], v[198:201], v[56:59]
	s_add_u32 s38, s38, 0x80000
	v_mfma_i32_16x16x64_i8 v[44:47], v[148:151], v[206:209], v[44:47]
	v_mfma_i32_16x16x64_i8 v[40:43], v[174:177], v[206:209], v[40:43]
	s_addc_u32 s39, s39, 0
	v_mfma_i32_16x16x64_i8 v[28:31], v[148:151], v[214:217], v[28:31]
	v_mfma_i32_16x16x64_i8 v[24:27], v[174:177], v[214:217], v[24:27]
	v_mfma_i32_16x16x64_i8 v[12:15], v[148:151], v[222:225], v[12:15]
	v_mfma_i32_16x16x64_i8 v[8:11], v[174:177], v[222:225], v[8:11]
	v_mfma_i32_16x16x64_i8 v[52:55], v[178:181], v[194:197], v[52:55]
	v_mfma_i32_16x16x64_i8 v[48:51], v[186:189], v[194:197], v[48:51]
	v_mfma_i32_16x16x64_i8 v[36:39], v[178:181], v[202:205], v[36:39]
	v_mfma_i32_16x16x64_i8 v[32:35], v[186:189], v[202:205], v[32:35]
	v_mfma_i32_16x16x64_i8 v[20:23], v[178:181], v[210:213], v[20:23]
	v_mfma_i32_16x16x64_i8 v[16:19], v[186:189], v[210:213], v[16:19]
	v_mfma_i32_16x16x64_i8 v[4:7], v[178:181], v[218:221], v[4:7]
	v_mfma_i32_16x16x64_i8 v[0:3], v[186:189], v[218:221], v[0:3]
	v_mfma_i32_16x16x64_i8 v[52:55], v[182:185], v[198:201], v[52:55]
	v_mfma_i32_16x16x64_i8 v[48:51], v[190:193], v[198:201], v[48:51]
	v_mfma_i32_16x16x64_i8 v[36:39], v[182:185], v[206:209], v[36:39]
	v_mfma_i32_16x16x64_i8 v[32:35], v[190:193], v[206:209], v[32:35]
	v_mfma_i32_16x16x64_i8 v[20:23], v[182:185], v[214:217], v[20:23]
	v_mfma_i32_16x16x64_i8 v[16:19], v[190:193], v[214:217], v[16:19]
	v_mfma_i32_16x16x64_i8 v[4:7], v[182:185], v[222:225], v[4:7]
	v_mfma_i32_16x16x64_i8 v[0:3], v[190:193], v[222:225], v[0:3]
	s_barrier
	ds_read_b128 v[194:197], v166 offset:32768
	ds_read_b128 v[198:201], v166 offset:33792
	ds_read_b128 v[202:205], v166 offset:34816
	ds_read_b128 v[206:209], v166 offset:35840
	ds_read_b128 v[210:213], v166 offset:36864
	ds_read_b128 v[214:217], v166 offset:37888
	ds_read_b128 v[218:221], v166 offset:38912
	ds_read_b128 v[222:225], v166 offset:39936
	ds_read_b128 v[144:147], v154
	ds_read_b128 v[148:151], v154 offset:1024
	ds_read_b128 v[170:173], v154 offset:2048
	ds_read_b128 v[174:177], v154 offset:3072
	v_add_u32_e32 v154, s66, v157
	ds_read_b128 v[178:181], v154
	ds_read_b128 v[182:185], v154 offset:1024
	ds_read_b128 v[186:189], v154 offset:2048
	ds_read_b128 v[190:193], v154 offset:3072
	s_mov_b32 m0, s47
	s_nop 0
	global_load_lds_dwordx4 v128, s[38:39]
	s_mov_b32 m0, s48
	s_nop 0
	global_load_lds_dwordx4 v132, s[38:39]
	s_waitcnt vmcnt(8)
	s_waitcnt lgkmcnt(0)
	s_barrier
	s_waitcnt lgkmcnt(0)
	v_mfma_i32_16x16x64_i8 v[124:127], v[144:147], v[194:197], v[124:127]
	v_mfma_i32_16x16x64_i8 v[120:123], v[170:173], v[194:197], v[120:123]
	v_mfma_i32_16x16x64_i8 v[108:111], v[144:147], v[202:205], v[108:111]
	v_mfma_i32_16x16x64_i8 v[104:107], v[170:173], v[202:205], v[104:107]
	s_add_i32 s38, s65, s44
	v_mfma_i32_16x16x64_i8 v[92:95], v[144:147], v[210:213], v[92:95]
	v_mfma_i32_16x16x64_i8 v[88:91], v[170:173], v[210:213], v[88:91]
	v_mfma_i32_16x16x64_i8 v[76:79], v[144:147], v[218:221], v[76:79]
	v_mfma_i32_16x16x64_i8 v[72:75], v[170:173], v[218:221], v[72:75]
	s_add_u32 s6, s6, 0x80080
	v_mfma_i32_16x16x64_i8 v[124:127], v[148:151], v[198:201], v[124:127]
	v_mfma_i32_16x16x64_i8 v[120:123], v[174:177], v[198:201], v[120:123]
	v_mfma_i32_16x16x64_i8 v[108:111], v[148:151], v[206:209], v[108:111]
	v_mfma_i32_16x16x64_i8 v[104:107], v[174:177], v[206:209], v[104:107]
	s_addc_u32 s7, s7, 0
	v_mfma_i32_16x16x64_i8 v[92:95], v[148:151], v[214:217], v[92:95]
	v_mfma_i32_16x16x64_i8 v[88:91], v[174:177], v[214:217], v[88:91]
	v_mfma_i32_16x16x64_i8 v[76:79], v[148:151], v[222:225], v[76:79]
	v_mfma_i32_16x16x64_i8 v[72:75], v[174:177], v[222:225], v[72:75]
	v_mfma_i32_16x16x64_i8 v[116:119], v[178:181], v[194:197], v[116:119]
	v_mfma_i32_16x16x64_i8 v[112:115], v[186:189], v[194:197], v[112:115]
	v_mfma_i32_16x16x64_i8 v[100:103], v[178:181], v[202:205], v[100:103]
	v_mfma_i32_16x16x64_i8 v[96:99], v[186:189], v[202:205], v[96:99]
	v_mfma_i32_16x16x64_i8 v[84:87], v[178:181], v[210:213], v[84:87]
	v_mfma_i32_16x16x64_i8 v[80:83], v[186:189], v[210:213], v[80:83]
	v_mfma_i32_16x16x64_i8 v[68:71], v[178:181], v[218:221], v[68:71]
	v_mfma_i32_16x16x64_i8 v[64:67], v[186:189], v[218:221], v[64:67]
	v_mfma_i32_16x16x64_i8 v[116:119], v[182:185], v[198:201], v[116:119]
	v_mfma_i32_16x16x64_i8 v[112:115], v[190:193], v[198:201], v[112:115]
	v_mfma_i32_16x16x64_i8 v[100:103], v[182:185], v[206:209], v[100:103]
	v_mfma_i32_16x16x64_i8 v[96:99], v[190:193], v[206:209], v[96:99]
	v_mfma_i32_16x16x64_i8 v[84:87], v[182:185], v[214:217], v[84:87]
	v_mfma_i32_16x16x64_i8 v[80:83], v[190:193], v[214:217], v[80:83]
	v_mfma_i32_16x16x64_i8 v[68:71], v[182:185], v[222:225], v[68:71]
	v_mfma_i32_16x16x64_i8 v[64:67], v[190:193], v[222:225], v[64:67]
	s_barrier
	ds_read_b128 v[194:197], v166 offset:49152
	ds_read_b128 v[198:201], v166 offset:50176
	ds_read_b128 v[202:205], v166 offset:51200
	ds_read_b128 v[206:209], v166 offset:52224
	ds_read_b128 v[210:213], v166 offset:53248
	ds_read_b128 v[214:217], v166 offset:54272
	ds_read_b128 v[218:221], v166 offset:55296
	ds_read_b128 v[222:225], v166 offset:56320
	s_mov_b32 m0, s38
	s_nop 0
	global_load_lds_dwordx4 v130, s[98:99]
	s_add_i32 m0, s38, 0x2000
	s_add_i32 s38, s66, s44
	global_load_lds_dwordx4 v134, s[98:99]
	s_mov_b32 m0, s38
	s_nop 0
	global_load_lds_dwordx4 v130, s[6:7]
	s_add_i32 m0, s38, 0x2000
	s_nop 0
	global_load_lds_dwordx4 v134, s[6:7]
	s_mov_b32 m0, s50
	s_nop 0
	global_load_lds_dwordx4 v128, s[100:101]
	s_mov_b32 m0, s51
	s_nop 0
	global_load_lds_dwordx4 v132, s[100:101]
	s_waitcnt vmcnt(8)
	s_waitcnt lgkmcnt(0)
	s_barrier
	s_waitcnt lgkmcnt(0)
	v_mfma_i32_16x16x64_i8 v[60:63], v[144:147], v[194:197], v[60:63]
	v_mfma_i32_16x16x64_i8 v[56:59], v[170:173], v[194:197], v[56:59]
	v_mfma_i32_16x16x64_i8 v[44:47], v[144:147], v[202:205], v[44:47]
	v_mfma_i32_16x16x64_i8 v[40:43], v[170:173], v[202:205], v[40:43]
	v_mfma_i32_16x16x64_i8 v[28:31], v[144:147], v[210:213], v[28:31]
	v_mfma_i32_16x16x64_i8 v[24:27], v[170:173], v[210:213], v[24:27]
	v_mfma_i32_16x16x64_i8 v[12:15], v[144:147], v[218:221], v[12:15]
	v_mfma_i32_16x16x64_i8 v[8:11], v[170:173], v[218:221], v[8:11]
	v_mfma_i32_16x16x64_i8 v[60:63], v[148:151], v[198:201], v[60:63]
	v_mfma_i32_16x16x64_i8 v[56:59], v[174:177], v[198:201], v[56:59]
	v_mfma_i32_16x16x64_i8 v[44:47], v[148:151], v[206:209], v[44:47]
	v_mfma_i32_16x16x64_i8 v[40:43], v[174:177], v[206:209], v[40:43]
	v_mfma_i32_16x16x64_i8 v[28:31], v[148:151], v[214:217], v[28:31]
	v_mfma_i32_16x16x64_i8 v[24:27], v[174:177], v[214:217], v[24:27]
	v_mfma_i32_16x16x64_i8 v[12:15], v[148:151], v[222:225], v[12:15]
	v_mfma_i32_16x16x64_i8 v[8:11], v[174:177], v[222:225], v[8:11]
	v_mfma_i32_16x16x64_i8 v[52:55], v[178:181], v[194:197], v[52:55]
	v_mfma_i32_16x16x64_i8 v[48:51], v[186:189], v[194:197], v[48:51]
	v_mfma_i32_16x16x64_i8 v[36:39], v[178:181], v[202:205], v[36:39]
	v_mfma_i32_16x16x64_i8 v[32:35], v[186:189], v[202:205], v[32:35]
	v_mfma_i32_16x16x64_i8 v[20:23], v[178:181], v[210:213], v[20:23]
	v_mfma_i32_16x16x64_i8 v[16:19], v[186:189], v[210:213], v[16:19]
	v_mfma_i32_16x16x64_i8 v[4:7], v[178:181], v[218:221], v[4:7]
	v_mfma_i32_16x16x64_i8 v[0:3], v[186:189], v[218:221], v[0:3]
	v_mfma_i32_16x16x64_i8 v[52:55], v[182:185], v[198:201], v[52:55]
	v_mfma_i32_16x16x64_i8 v[48:51], v[190:193], v[198:201], v[48:51]
	v_mfma_i32_16x16x64_i8 v[36:39], v[182:185], v[206:209], v[36:39]
	v_mfma_i32_16x16x64_i8 v[32:35], v[190:193], v[206:209], v[32:35]
	v_mfma_i32_16x16x64_i8 v[20:23], v[182:185], v[214:217], v[20:23]
	v_mfma_i32_16x16x64_i8 v[16:19], v[190:193], v[214:217], v[16:19]
	v_mfma_i32_16x16x64_i8 v[4:7], v[182:185], v[222:225], v[4:7]
	v_mfma_i32_16x16x64_i8 v[0:3], v[190:193], v[222:225], v[0:3]
	s_barrier
	s_add_i32 s64, s64, 2
	s_add_u32 s62, s62, 0x100
	s_addc_u32 s63, s63, 0
	s_add_u32 s4, s4, 0x100
	s_addc_u32 s5, s5, 0
	s_cmp_gt_u32 s64, 29
	s_cbranch_scc0 .LBB0_550
	s_setprio 0
	s_and_b64 vcc, exec, s[18:19]
	s_cbranch_vccz .LBB0_553
	s_barrier

.Lsp_skip5:
.LBB0_635:
	ds_read_b128 v[112:115], v193
	ds_read_b128 v[124:127], v193 offset:1024
	ds_read_b128 v[136:139], v193 offset:2048
	ds_read_b128 v[140:143], v193 offset:3072
	ds_read_b128 v[144:147], v194
	ds_read_b128 v[148:151], v194 offset:1024
	ds_read_b128 v[168:171], v194 offset:2048
	ds_read_b128 v[172:175], v194 offset:3072
	ds_read_b128 v[176:179], v195
	ds_read_b128 v[180:183], v195 offset:1024
	ds_read_b128 v[184:187], v195 offset:2048
	ds_read_b128 v[200:203], v195 offset:3072
	ds_read_b128 v[204:207], v195 offset:4096
	ds_read_b128 v[208:211], v195 offset:5120
	ds_read_b128 v[212:215], v195 offset:6144
	ds_read_b128 v[216:219], v195 offset:7168
	s_add_u32 s34, s30, 0xffbf8080
	s_addc_u32 s35, s31, -1
	s_cmpk_eq_i32 s58, 0xfc
	s_cselect_b32 s37, s21, s35
	s_cselect_b32 s36, s27, s34
	s_cselect_b32 s35, s19, s57
	s_cselect_b32 s34, s55, s56
	s_add_i32 m0, s29, 0xc000
	s_nop 0
	global_load_lds_dwordx4 v162, s[30:31]
	s_add_i32 m0, s29, 0xe000
	s_nop 0
	global_load_lds_dwordx4 v160, s[30:31]
	s_waitcnt vmcnt(8)
	s_waitcnt lgkmcnt(0)
	s_barrier
	s_waitcnt lgkmcnt(0)
	v_mfma_f32_16x16x32_bf16 v[132:135], v[112:115], v[176:179], v[132:135]
	v_mfma_f32_16x16x32_bf16 v[128:131], v[136:139], v[176:179], v[128:131]
	v_mfma_f32_16x16x32_bf16 v[108:111], v[112:115], v[184:187], v[108:111]
	v_mfma_f32_16x16x32_bf16 v[104:107], v[136:139], v[184:187], v[104:107]
	s_add_u32 s98, s34, s14
	s_addc_u32 s99, s35, s15
	s_add_i32 s59, s50, s41
	v_mfma_f32_16x16x32_bf16 v[92:95], v[112:115], v[204:207], v[92:95]
	s_add_u32 s100, s36, s14
	s_addc_u32 s101, s37, s15
	v_mfma_f32_16x16x32_bf16 v[88:91], v[136:139], v[204:207], v[88:91]
	v_mfma_f32_16x16x32_bf16 v[76:79], v[112:115], v[212:215], v[76:79]
	v_mfma_f32_16x16x32_bf16 v[72:75], v[136:139], v[212:215], v[72:75]
	s_add_u32 s60, s34, 0x400000
	v_mfma_f32_16x16x32_bf16 v[132:135], v[124:127], v[180:183], v[132:135]
	v_mfma_f32_16x16x32_bf16 v[128:131], v[140:143], v[180:183], v[128:131]
	v_mfma_f32_16x16x32_bf16 v[108:111], v[124:127], v[200:203], v[108:111]
	v_mfma_f32_16x16x32_bf16 v[104:107], v[140:143], v[200:203], v[104:107]
	s_addc_u32 s61, s35, 0
	v_mfma_f32_16x16x32_bf16 v[92:95], v[124:127], v[208:211], v[92:95]
	v_mfma_f32_16x16x32_bf16 v[88:91], v[140:143], v[208:211], v[88:91]
	v_mfma_f32_16x16x32_bf16 v[76:79], v[124:127], v[216:219], v[76:79]
	v_mfma_f32_16x16x32_bf16 v[72:75], v[140:143], v[216:219], v[72:75]
	v_mfma_f32_16x16x32_bf16 v[120:123], v[144:147], v[176:179], v[120:123]
	v_mfma_f32_16x16x32_bf16 v[116:119], v[168:171], v[176:179], v[116:119]
	v_mfma_f32_16x16x32_bf16 v[100:103], v[144:147], v[184:187], v[100:103]
	v_mfma_f32_16x16x32_bf16 v[96:99], v[168:171], v[184:187], v[96:99]
	v_mfma_f32_16x16x32_bf16 v[84:87], v[144:147], v[204:207], v[84:87]
	v_mfma_f32_16x16x32_bf16 v[80:83], v[168:171], v[204:207], v[80:83]
	v_mfma_f32_16x16x32_bf16 v[68:71], v[144:147], v[212:215], v[68:71]
	v_mfma_f32_16x16x32_bf16 v[64:67], v[168:171], v[212:215], v[64:67]
	v_mfma_f32_16x16x32_bf16 v[120:123], v[148:151], v[180:183], v[120:123]
	v_mfma_f32_16x16x32_bf16 v[116:119], v[172:175], v[180:183], v[116:119]
	v_mfma_f32_16x16x32_bf16 v[100:103], v[148:151], v[200:203], v[100:103]
	v_mfma_f32_16x16x32_bf16 v[96:99], v[172:175], v[200:203], v[96:99]
	v_mfma_f32_16x16x32_bf16 v[84:87], v[148:151], v[208:211], v[84:87]
	v_mfma_f32_16x16x32_bf16 v[80:83], v[172:175], v[208:211], v[80:83]
	v_mfma_f32_16x16x32_bf16 v[68:71], v[148:151], v[216:219], v[68:71]
	v_mfma_f32_16x16x32_bf16 v[64:67], v[172:175], v[216:219], v[64:67]
	s_barrier
	ds_read_b128 v[176:179], v195 offset:16384
	ds_read_b128 v[180:183], v195 offset:17408
	ds_read_b128 v[184:187], v195 offset:18432
	ds_read_b128 v[200:203], v195 offset:19456
	ds_read_b128 v[204:207], v195 offset:20480
	ds_read_b128 v[208:211], v195 offset:21504
	ds_read_b128 v[212:215], v195 offset:22528
	ds_read_b128 v[216:219], v195 offset:23552
	s_mov_b32 m0, s59
	s_nop 0
	global_load_lds_dwordx4 v154, s[34:35]
	s_add_i32 m0, s59, 0x2000
	s_add_i32 s59, s51, s41
	global_load_lds_dwordx4 v158, s[34:35]
	s_mov_b32 m0, s59
	s_nop 0
	global_load_lds_dwordx4 v154, s[60:61]
	s_add_i32 m0, s59, 0x2000
	s_nop 0
	global_load_lds_dwordx4 v158, s[60:61]
	s_mov_b32 m0, s29
	s_nop 0
	global_load_lds_dwordx4 v152, s[36:37]
	s_mov_b32 m0, s42
	s_nop 0
	global_load_lds_dwordx4 v156, s[36:37]
	s_waitcnt vmcnt(8)
	s_waitcnt lgkmcnt(0)
	s_barrier
	s_waitcnt lgkmcnt(0)
	v_mfma_f32_16x16x32_bf16 v[60:63], v[112:115], v[176:179], v[60:63]
	v_mfma_f32_16x16x32_bf16 v[56:59], v[136:139], v[176:179], v[56:59]
	v_mfma_f32_16x16x32_bf16 v[44:47], v[112:115], v[184:187], v[44:47]
	v_mfma_f32_16x16x32_bf16 v[40:43], v[136:139], v[184:187], v[40:43]
	s_add_i32 s59, 0, 0x18000
	v_mfma_f32_16x16x32_bf16 v[28:31], v[112:115], v[204:207], v[28:31]
	v_mfma_f32_16x16x32_bf16 v[24:27], v[136:139], v[204:207], v[24:27]
	s_add_i32 s60, 0, 0x1c000
	v_mfma_f32_16x16x32_bf16 v[12:15], v[112:115], v[212:215], v[12:15]
	v_mfma_f32_16x16x32_bf16 v[8:11], v[136:139], v[212:215], v[8:11]
	s_add_u32 s36, s36, 0x408000
	v_mfma_f32_16x16x32_bf16 v[60:63], v[124:127], v[180:183], v[60:63]
	v_mfma_f32_16x16x32_bf16 v[56:59], v[140:143], v[180:183], v[56:59]
	s_addc_u32 s37, s37, 0
	v_mfma_f32_16x16x32_bf16 v[44:47], v[124:127], v[200:203], v[44:47]
	v_mfma_f32_16x16x32_bf16 v[40:43], v[140:143], v[200:203], v[40:43]
	v_mfma_f32_16x16x32_bf16 v[28:31], v[124:127], v[208:211], v[28:31]
	v_mfma_f32_16x16x32_bf16 v[24:27], v[140:143], v[208:211], v[24:27]
	v_mfma_f32_16x16x32_bf16 v[12:15], v[124:127], v[216:219], v[12:15]
	v_mfma_f32_16x16x32_bf16 v[8:11], v[140:143], v[216:219], v[8:11]
	v_mfma_f32_16x16x32_bf16 v[52:55], v[144:147], v[176:179], v[52:55]
	v_mfma_f32_16x16x32_bf16 v[48:51], v[168:171], v[176:179], v[48:51]
	v_mfma_f32_16x16x32_bf16 v[36:39], v[144:147], v[184:187], v[36:39]
	v_mfma_f32_16x16x32_bf16 v[32:35], v[168:171], v[184:187], v[32:35]
	v_mfma_f32_16x16x32_bf16 v[20:23], v[144:147], v[204:207], v[20:23]
	v_mfma_f32_16x16x32_bf16 v[16:19], v[168:171], v[204:207], v[16:19]
	v_mfma_f32_16x16x32_bf16 v[4:7], v[144:147], v[212:215], v[4:7]
	v_mfma_f32_16x16x32_bf16 v[0:3], v[168:171], v[212:215], v[0:3]
	v_mfma_f32_16x16x32_bf16 v[52:55], v[148:151], v[180:183], v[52:55]
	v_mfma_f32_16x16x32_bf16 v[48:51], v[172:175], v[180:183], v[48:51]
	v_mfma_f32_16x16x32_bf16 v[36:39], v[148:151], v[200:203], v[36:39]
	v_mfma_f32_16x16x32_bf16 v[32:35], v[172:175], v[200:203], v[32:35]
	v_mfma_f32_16x16x32_bf16 v[20:23], v[148:151], v[208:211], v[20:23]
	v_mfma_f32_16x16x32_bf16 v[16:19], v[172:175], v[208:211], v[16:19]
	v_mfma_f32_16x16x32_bf16 v[4:7], v[148:151], v[216:219], v[4:7]
	v_mfma_f32_16x16x32_bf16 v[0:3], v[172:175], v[216:219], v[0:3]
	s_barrier
	ds_read_b128 v[176:179], v195 offset:32768
	ds_read_b128 v[180:183], v195 offset:33792
	ds_read_b128 v[184:187], v195 offset:34816
	ds_read_b128 v[200:203], v195 offset:35840
	ds_read_b128 v[204:207], v195 offset:36864
	ds_read_b128 v[208:211], v195 offset:37888
	ds_read_b128 v[212:215], v195 offset:38912
	ds_read_b128 v[216:219], v195 offset:39936
	v_add_u32_e32 v140, s59, v191
	v_add_u32_e32 v172, s60, v191
	ds_read_b128 v[112:115], v140
	ds_read_b128 v[124:127], v140 offset:1024
	ds_read_b128 v[136:139], v140 offset:2048
	ds_read_b128 v[140:143], v140 offset:3072
	ds_read_b128 v[144:147], v172
	ds_read_b128 v[148:151], v172 offset:1024
	ds_read_b128 v[168:171], v172 offset:2048
	ds_read_b128 v[172:175], v172 offset:3072
	s_mov_b32 m0, s43
	s_nop 0
	global_load_lds_dwordx4 v152, s[36:37]
	s_mov_b32 m0, s44
	s_nop 0
	global_load_lds_dwordx4 v156, s[36:37]
	s_waitcnt vmcnt(8)
	s_waitcnt lgkmcnt(0)
	s_barrier
	s_waitcnt lgkmcnt(0)
	v_mfma_f32_16x16x32_bf16 v[132:135], v[112:115], v[176:179], v[132:135]
	v_mfma_f32_16x16x32_bf16 v[128:131], v[136:139], v[176:179], v[128:131]
	v_mfma_f32_16x16x32_bf16 v[108:111], v[112:115], v[184:187], v[108:111]
	v_mfma_f32_16x16x32_bf16 v[104:107], v[136:139], v[184:187], v[104:107]
	s_add_i32 s36, s59, s41
	v_mfma_f32_16x16x32_bf16 v[92:95], v[112:115], v[204:207], v[92:95]
	v_mfma_f32_16x16x32_bf16 v[88:91], v[136:139], v[204:207], v[88:91]
	v_mfma_f32_16x16x32_bf16 v[76:79], v[112:115], v[212:215], v[76:79]
	v_mfma_f32_16x16x32_bf16 v[72:75], v[136:139], v[212:215], v[72:75]
	s_add_u32 s34, s34, 0x400080
	v_mfma_f32_16x16x32_bf16 v[132:135], v[124:127], v[180:183], v[132:135]
	v_mfma_f32_16x16x32_bf16 v[128:131], v[140:143], v[180:183], v[128:131]
	v_mfma_f32_16x16x32_bf16 v[108:111], v[124:127], v[200:203], v[108:111]
	v_mfma_f32_16x16x32_bf16 v[104:107], v[140:143], v[200:203], v[104:107]
	s_addc_u32 s35, s35, 0
	v_mfma_f32_16x16x32_bf16 v[92:95], v[124:127], v[208:211], v[92:95]
	v_mfma_f32_16x16x32_bf16 v[88:91], v[140:143], v[208:211], v[88:91]
	v_mfma_f32_16x16x32_bf16 v[76:79], v[124:127], v[216:219], v[76:79]
	v_mfma_f32_16x16x32_bf16 v[72:75], v[140:143], v[216:219], v[72:75]
	v_mfma_f32_16x16x32_bf16 v[120:123], v[144:147], v[176:179], v[120:123]
	v_mfma_f32_16x16x32_bf16 v[116:119], v[168:171], v[176:179], v[116:119]
	v_mfma_f32_16x16x32_bf16 v[100:103], v[144:147], v[184:187], v[100:103]
	v_mfma_f32_16x16x32_bf16 v[96:99], v[168:171], v[184:187], v[96:99]
	v_mfma_f32_16x16x32_bf16 v[84:87], v[144:147], v[204:207], v[84:87]
	v_mfma_f32_16x16x32_bf16 v[80:83], v[168:171], v[204:207], v[80:83]
	v_mfma_f32_16x16x32_bf16 v[68:71], v[144:147], v[212:215], v[68:71]
	v_mfma_f32_16x16x32_bf16 v[64:67], v[168:171], v[212:215], v[64:67]
	v_mfma_f32_16x16x32_bf16 v[120:123], v[148:151], v[180:183], v[120:123]
	v_mfma_f32_16x16x32_bf16 v[116:119], v[172:175], v[180:183], v[116:119]
	v_mfma_f32_16x16x32_bf16 v[100:103], v[148:151], v[200:203], v[100:103]
	v_mfma_f32_16x16x32_bf16 v[96:99], v[172:175], v[200:203], v[96:99]
	v_mfma_f32_16x16x32_bf16 v[84:87], v[148:151], v[208:211], v[84:87]
	v_mfma_f32_16x16x32_bf16 v[80:83], v[172:175], v[208:211], v[80:83]
	v_mfma_f32_16x16x32_bf16 v[68:71], v[148:151], v[216:219], v[68:71]
	v_mfma_f32_16x16x32_bf16 v[64:67], v[172:175], v[216:219], v[64:67]
	s_barrier
	ds_read_b128 v[176:179], v195 offset:49152
	ds_read_b128 v[180:183], v195 offset:50176
	ds_read_b128 v[184:187], v195 offset:51200
	ds_read_b128 v[200:203], v195 offset:52224
	ds_read_b128 v[204:207], v195 offset:53248
	ds_read_b128 v[208:211], v195 offset:54272
	ds_read_b128 v[212:215], v195 offset:55296
	ds_read_b128 v[216:219], v195 offset:56320
	s_mov_b32 m0, s36
	s_nop 0
	global_load_lds_dwordx4 v154, s[98:99]
	s_add_i32 m0, s36, 0x2000
	s_add_i32 s36, s60, s41
	global_load_lds_dwordx4 v158, s[98:99]
	s_mov_b32 m0, s36
	s_nop 0
	global_load_lds_dwordx4 v154, s[34:35]
	s_add_i32 m0, s36, 0x2000
	s_nop 0
	global_load_lds_dwordx4 v158, s[34:35]
	s_mov_b32 m0, s46
	s_nop 0
	global_load_lds_dwordx4 v152, s[100:101]
	s_mov_b32 m0, s47
	s_nop 0
	global_load_lds_dwordx4 v156, s[100:101]
	s_waitcnt vmcnt(8)
	s_waitcnt lgkmcnt(0)
	s_barrier
	s_waitcnt lgkmcnt(0)
	v_mfma_f32_16x16x32_bf16 v[60:63], v[112:115], v[176:179], v[60:63]
	v_mfma_f32_16x16x32_bf16 v[56:59], v[136:139], v[176:179], v[56:59]
	v_mfma_f32_16x16x32_bf16 v[44:47], v[112:115], v[184:187], v[44:47]
	v_mfma_f32_16x16x32_bf16 v[40:43], v[136:139], v[184:187], v[40:43]
	v_mfma_f32_16x16x32_bf16 v[28:31], v[112:115], v[204:207], v[28:31]
	v_mfma_f32_16x16x32_bf16 v[24:27], v[136:139], v[204:207], v[24:27]
	v_mfma_f32_16x16x32_bf16 v[12:15], v[112:115], v[212:215], v[12:15]
	v_mfma_f32_16x16x32_bf16 v[8:11], v[136:139], v[212:215], v[8:11]
	v_mfma_f32_16x16x32_bf16 v[60:63], v[124:127], v[180:183], v[60:63]
	v_mfma_f32_16x16x32_bf16 v[56:59], v[140:143], v[180:183], v[56:59]
	v_mfma_f32_16x16x32_bf16 v[44:47], v[124:127], v[200:203], v[44:47]
	v_mfma_f32_16x16x32_bf16 v[40:43], v[140:143], v[200:203], v[40:43]
	v_mfma_f32_16x16x32_bf16 v[28:31], v[124:127], v[208:211], v[28:31]
	v_mfma_f32_16x16x32_bf16 v[24:27], v[140:143], v[208:211], v[24:27]
	v_mfma_f32_16x16x32_bf16 v[12:15], v[124:127], v[216:219], v[12:15]
	v_mfma_f32_16x16x32_bf16 v[8:11], v[140:143], v[216:219], v[8:11]
	v_mfma_f32_16x16x32_bf16 v[52:55], v[144:147], v[176:179], v[52:55]
	v_mfma_f32_16x16x32_bf16 v[48:51], v[168:171], v[176:179], v[48:51]
	v_mfma_f32_16x16x32_bf16 v[36:39], v[144:147], v[184:187], v[36:39]
	v_mfma_f32_16x16x32_bf16 v[32:35], v[168:171], v[184:187], v[32:35]
	v_mfma_f32_16x16x32_bf16 v[20:23], v[144:147], v[204:207], v[20:23]
	v_mfma_f32_16x16x32_bf16 v[16:19], v[168:171], v[204:207], v[16:19]
	v_mfma_f32_16x16x32_bf16 v[4:7], v[144:147], v[212:215], v[4:7]
	v_mfma_f32_16x16x32_bf16 v[0:3], v[168:171], v[212:215], v[0:3]
	v_mfma_f32_16x16x32_bf16 v[52:55], v[148:151], v[180:183], v[52:55]
	v_mfma_f32_16x16x32_bf16 v[48:51], v[172:175], v[180:183], v[48:51]
	v_mfma_f32_16x16x32_bf16 v[36:39], v[148:151], v[200:203], v[36:39]
	v_mfma_f32_16x16x32_bf16 v[32:35], v[172:175], v[200:203], v[32:35]
	v_mfma_f32_16x16x32_bf16 v[20:23], v[148:151], v[208:211], v[20:23]
	v_mfma_f32_16x16x32_bf16 v[16:19], v[172:175], v[208:211], v[16:19]
	v_mfma_f32_16x16x32_bf16 v[4:7], v[148:151], v[216:219], v[4:7]
	v_mfma_f32_16x16x32_bf16 v[0:3], v[172:175], v[216:219], v[0:3]
	s_barrier
	s_add_i32 s58, s58, 2
	s_add_u32 s56, s56, 0x100
	s_addc_u32 s57, s57, 0
	s_add_u32 s30, s30, 0x100
	s_addc_u32 s31, s31, 0
	s_cmpk_gt_u32 s58, 0xfd
	s_cbranch_scc0 .LBB0_635
	s_setprio 0
	s_and_b64 vcc, exec, s[16:17]
	s_cbranch_vccz .LBB0_638
	s_barrier

.Lsp_skip6:
.LBB0_726:
	ds_read_b128 v[144:147], v161
	ds_read_b128 v[148:151], v161 offset:1024
	ds_read_b128 v[168:171], v161 offset:2048
	ds_read_b128 v[172:175], v161 offset:3072
	ds_read_b128 v[176:179], v163
	ds_read_b128 v[180:183], v163 offset:1024
	ds_read_b128 v[184:187], v163 offset:2048
	ds_read_b128 v[188:191], v163 offset:3072
	ds_read_b128 v[192:195], v165
	ds_read_b128 v[196:199], v165 offset:1024
	ds_read_b128 v[200:203], v165 offset:2048
	ds_read_b128 v[204:207], v165 offset:3072
	ds_read_b128 v[208:211], v165 offset:4096
	ds_read_b128 v[212:215], v165 offset:5120
	ds_read_b128 v[216:219], v165 offset:6144
	ds_read_b128 v[220:223], v165 offset:7168
	s_add_u32 s6, s4, 0xfff80080
	s_addc_u32 s7, s5, -1
	s_cmp_eq_u32 s54, 28
	s_cselect_b32 s29, s1, s7
	s_cselect_b32 s28, s23, s6
	s_cselect_b32 s7, s21, s53
	s_cselect_b32 s6, s51, s52
	s_add_i32 m0, s38, 0xc000
	s_nop 0
	global_load_lds_dwordx4 v138, s[4:5]
	s_add_i32 m0, s38, 0xe000
	s_nop 0
	global_load_lds_dwordx4 v136, s[4:5]
	s_waitcnt vmcnt(8)
	s_waitcnt lgkmcnt(0)
	s_barrier
	s_waitcnt lgkmcnt(0)
	v_mfma_i32_16x16x64_i8 v[124:127], v[144:147], v[192:195], v[124:127]
	v_mfma_i32_16x16x64_i8 v[120:123], v[168:171], v[192:195], v[120:123]
	v_mfma_i32_16x16x64_i8 v[108:111], v[144:147], v[200:203], v[108:111]
	v_mfma_i32_16x16x64_i8 v[104:107], v[168:171], v[200:203], v[104:107]
	s_add_u32 s98, s6, s16
	s_addc_u32 s99, s7, s17
	s_add_i32 s55, s46, s35
	v_mfma_i32_16x16x64_i8 v[92:95], v[144:147], v[208:211], v[92:95]
	s_add_u32 s100, s28, s16
	s_addc_u32 s101, s29, s17
	v_mfma_i32_16x16x64_i8 v[88:91], v[168:171], v[208:211], v[88:91]
	v_mfma_i32_16x16x64_i8 v[76:79], v[144:147], v[216:219], v[76:79]
	v_mfma_i32_16x16x64_i8 v[72:75], v[168:171], v[216:219], v[72:75]
	s_add_u32 s56, s6, 0x80000
	v_mfma_i32_16x16x64_i8 v[124:127], v[148:151], v[196:199], v[124:127]
	v_mfma_i32_16x16x64_i8 v[120:123], v[172:175], v[196:199], v[120:123]
	v_mfma_i32_16x16x64_i8 v[108:111], v[148:151], v[204:207], v[108:111]
	v_mfma_i32_16x16x64_i8 v[104:107], v[172:175], v[204:207], v[104:107]
	s_addc_u32 s57, s7, 0
	v_mfma_i32_16x16x64_i8 v[92:95], v[148:151], v[212:215], v[92:95]
	v_mfma_i32_16x16x64_i8 v[88:91], v[172:175], v[212:215], v[88:91]
	v_mfma_i32_16x16x64_i8 v[76:79], v[148:151], v[220:223], v[76:79]
	v_mfma_i32_16x16x64_i8 v[72:75], v[172:175], v[220:223], v[72:75]
	v_mfma_i32_16x16x64_i8 v[116:119], v[176:179], v[192:195], v[116:119]
	v_mfma_i32_16x16x64_i8 v[112:115], v[184:187], v[192:195], v[112:115]
	v_mfma_i32_16x16x64_i8 v[100:103], v[176:179], v[200:203], v[100:103]
	v_mfma_i32_16x16x64_i8 v[96:99], v[184:187], v[200:203], v[96:99]
	v_mfma_i32_16x16x64_i8 v[84:87], v[176:179], v[208:211], v[84:87]
	v_mfma_i32_16x16x64_i8 v[80:83], v[184:187], v[208:211], v[80:83]
	v_mfma_i32_16x16x64_i8 v[68:71], v[176:179], v[216:219], v[68:71]
	v_mfma_i32_16x16x64_i8 v[64:67], v[184:187], v[216:219], v[64:67]
	v_mfma_i32_16x16x64_i8 v[116:119], v[180:183], v[196:199], v[116:119]
	v_mfma_i32_16x16x64_i8 v[112:115], v[188:191], v[196:199], v[112:115]
	v_mfma_i32_16x16x64_i8 v[100:103], v[180:183], v[204:207], v[100:103]
	v_mfma_i32_16x16x64_i8 v[96:99], v[188:191], v[204:207], v[96:99]
	v_mfma_i32_16x16x64_i8 v[84:87], v[180:183], v[212:215], v[84:87]
	v_mfma_i32_16x16x64_i8 v[80:83], v[188:191], v[212:215], v[80:83]
	v_mfma_i32_16x16x64_i8 v[68:71], v[180:183], v[220:223], v[68:71]
	v_mfma_i32_16x16x64_i8 v[64:67], v[188:191], v[220:223], v[64:67]
	s_barrier
	ds_read_b128 v[192:195], v165 offset:16384
	ds_read_b128 v[196:199], v165 offset:17408
	ds_read_b128 v[200:203], v165 offset:18432
	ds_read_b128 v[204:207], v165 offset:19456
	ds_read_b128 v[208:211], v165 offset:20480
	ds_read_b128 v[212:215], v165 offset:21504
	ds_read_b128 v[216:219], v165 offset:22528
	ds_read_b128 v[220:223], v165 offset:23552
	s_mov_b32 m0, s55
	s_nop 0
	global_load_lds_dwordx4 v132, s[6:7]
	s_add_i32 m0, s55, 0x2000
	s_add_i32 s55, s47, s35
	global_load_lds_dwordx4 v128, s[6:7]
	s_mov_b32 m0, s55
	s_nop 0
	global_load_lds_dwordx4 v132, s[56:57]
	s_add_i32 m0, s55, 0x2000
	s_nop 0
	global_load_lds_dwordx4 v128, s[56:57]
	s_mov_b32 m0, s38
	s_nop 0
	global_load_lds_dwordx4 v134, s[28:29]
	s_mov_b32 m0, s39
	s_nop 0
	global_load_lds_dwordx4 v130, s[28:29]
	s_waitcnt vmcnt(8)
	s_waitcnt lgkmcnt(0)
	s_barrier
	s_waitcnt lgkmcnt(0)
	v_mfma_i32_16x16x64_i8 v[60:63], v[144:147], v[192:195], v[60:63]
	v_mfma_i32_16x16x64_i8 v[56:59], v[168:171], v[192:195], v[56:59]
	v_mfma_i32_16x16x64_i8 v[44:47], v[144:147], v[200:203], v[44:47]
	v_mfma_i32_16x16x64_i8 v[40:43], v[168:171], v[200:203], v[40:43]
	s_add_i32 s55, 0, 0x18000
	v_mfma_i32_16x16x64_i8 v[28:31], v[144:147], v[208:211], v[28:31]
	v_mfma_i32_16x16x64_i8 v[24:27], v[168:171], v[208:211], v[24:27]
	v_add_u32_e32 v154, s55, v157
	v_mfma_i32_16x16x64_i8 v[12:15], v[144:147], v[216:219], v[12:15]
	v_mfma_i32_16x16x64_i8 v[8:11], v[168:171], v[216:219], v[8:11]
	s_add_i32 s56, 0, 0x1c000
	v_mfma_i32_16x16x64_i8 v[60:63], v[148:151], v[196:199], v[60:63]
	v_mfma_i32_16x16x64_i8 v[56:59], v[172:175], v[196:199], v[56:59]
	s_add_u32 s28, s28, 0x80000
	v_mfma_i32_16x16x64_i8 v[44:47], v[148:151], v[204:207], v[44:47]
	v_mfma_i32_16x16x64_i8 v[40:43], v[172:175], v[204:207], v[40:43]
	s_addc_u32 s29, s29, 0
	v_mfma_i32_16x16x64_i8 v[28:31], v[148:151], v[212:215], v[28:31]
	v_mfma_i32_16x16x64_i8 v[24:27], v[172:175], v[212:215], v[24:27]
	v_mfma_i32_16x16x64_i8 v[12:15], v[148:151], v[220:223], v[12:15]
	v_mfma_i32_16x16x64_i8 v[8:11], v[172:175], v[220:223], v[8:11]
	v_mfma_i32_16x16x64_i8 v[52:55], v[176:179], v[192:195], v[52:55]
	v_mfma_i32_16x16x64_i8 v[48:51], v[184:187], v[192:195], v[48:51]
	v_mfma_i32_16x16x64_i8 v[36:39], v[176:179], v[200:203], v[36:39]
	v_mfma_i32_16x16x64_i8 v[32:35], v[184:187], v[200:203], v[32:35]
	v_mfma_i32_16x16x64_i8 v[20:23], v[176:179], v[208:211], v[20:23]
	v_mfma_i32_16x16x64_i8 v[16:19], v[184:187], v[208:211], v[16:19]
	v_mfma_i32_16x16x64_i8 v[4:7], v[176:179], v[216:219], v[4:7]
	v_mfma_i32_16x16x64_i8 v[0:3], v[184:187], v[216:219], v[0:3]
	v_mfma_i32_16x16x64_i8 v[52:55], v[180:183], v[196:199], v[52:55]
	v_mfma_i32_16x16x64_i8 v[48:51], v[188:191], v[196:199], v[48:51]
	v_mfma_i32_16x16x64_i8 v[36:39], v[180:183], v[204:207], v[36:39]
	v_mfma_i32_16x16x64_i8 v[32:35], v[188:191], v[204:207], v[32:35]
	v_mfma_i32_16x16x64_i8 v[20:23], v[180:183], v[212:215], v[20:23]
	v_mfma_i32_16x16x64_i8 v[16:19], v[188:191], v[212:215], v[16:19]
	v_mfma_i32_16x16x64_i8 v[4:7], v[180:183], v[220:223], v[4:7]
	v_mfma_i32_16x16x64_i8 v[0:3], v[188:191], v[220:223], v[0:3]
	s_barrier
	ds_read_b128 v[192:195], v165 offset:32768
	ds_read_b128 v[196:199], v165 offset:33792
	ds_read_b128 v[200:203], v165 offset:34816
	ds_read_b128 v[204:207], v165 offset:35840
	ds_read_b128 v[208:211], v165 offset:36864
	ds_read_b128 v[212:215], v165 offset:37888
	ds_read_b128 v[216:219], v165 offset:38912
	ds_read_b128 v[220:223], v165 offset:39936
	ds_read_b128 v[144:147], v154
	ds_read_b128 v[148:151], v154 offset:1024
	ds_read_b128 v[168:171], v154 offset:2048
	ds_read_b128 v[172:175], v154 offset:3072
	v_add_u32_e32 v154, s56, v157
	ds_read_b128 v[176:179], v154
	ds_read_b128 v[180:183], v154 offset:1024
	ds_read_b128 v[184:187], v154 offset:2048
	ds_read_b128 v[188:191], v154 offset:3072
	s_mov_b32 m0, s40
	s_nop 0
	global_load_lds_dwordx4 v134, s[28:29]
	s_mov_b32 m0, s41
	s_nop 0
	global_load_lds_dwordx4 v130, s[28:29]
	s_waitcnt vmcnt(8)
	s_waitcnt lgkmcnt(0)
	s_barrier
	s_waitcnt lgkmcnt(0)
	v_mfma_i32_16x16x64_i8 v[124:127], v[144:147], v[192:195], v[124:127]
	v_mfma_i32_16x16x64_i8 v[120:123], v[168:171], v[192:195], v[120:123]
	v_mfma_i32_16x16x64_i8 v[108:111], v[144:147], v[200:203], v[108:111]
	v_mfma_i32_16x16x64_i8 v[104:107], v[168:171], v[200:203], v[104:107]
	s_add_i32 s28, s55, s35
	v_mfma_i32_16x16x64_i8 v[92:95], v[144:147], v[208:211], v[92:95]
	v_mfma_i32_16x16x64_i8 v[88:91], v[168:171], v[208:211], v[88:91]
	v_mfma_i32_16x16x64_i8 v[76:79], v[144:147], v[216:219], v[76:79]
	v_mfma_i32_16x16x64_i8 v[72:75], v[168:171], v[216:219], v[72:75]
	s_add_u32 s6, s6, 0x80080
	v_mfma_i32_16x16x64_i8 v[124:127], v[148:151], v[196:199], v[124:127]
	v_mfma_i32_16x16x64_i8 v[120:123], v[172:175], v[196:199], v[120:123]
	v_mfma_i32_16x16x64_i8 v[108:111], v[148:151], v[204:207], v[108:111]
	v_mfma_i32_16x16x64_i8 v[104:107], v[172:175], v[204:207], v[104:107]
	s_addc_u32 s7, s7, 0
	v_mfma_i32_16x16x64_i8 v[92:95], v[148:151], v[212:215], v[92:95]
	v_mfma_i32_16x16x64_i8 v[88:91], v[172:175], v[212:215], v[88:91]
	v_mfma_i32_16x16x64_i8 v[76:79], v[148:151], v[220:223], v[76:79]
	v_mfma_i32_16x16x64_i8 v[72:75], v[172:175], v[220:223], v[72:75]
	v_mfma_i32_16x16x64_i8 v[116:119], v[176:179], v[192:195], v[116:119]
	v_mfma_i32_16x16x64_i8 v[112:115], v[184:187], v[192:195], v[112:115]
	v_mfma_i32_16x16x64_i8 v[100:103], v[176:179], v[200:203], v[100:103]
	v_mfma_i32_16x16x64_i8 v[96:99], v[184:187], v[200:203], v[96:99]
	v_mfma_i32_16x16x64_i8 v[84:87], v[176:179], v[208:211], v[84:87]
	v_mfma_i32_16x16x64_i8 v[80:83], v[184:187], v[208:211], v[80:83]
	v_mfma_i32_16x16x64_i8 v[68:71], v[176:179], v[216:219], v[68:71]
	v_mfma_i32_16x16x64_i8 v[64:67], v[184:187], v[216:219], v[64:67]
	v_mfma_i32_16x16x64_i8 v[116:119], v[180:183], v[196:199], v[116:119]
	v_mfma_i32_16x16x64_i8 v[112:115], v[188:191], v[196:199], v[112:115]
	v_mfma_i32_16x16x64_i8 v[100:103], v[180:183], v[204:207], v[100:103]
	v_mfma_i32_16x16x64_i8 v[96:99], v[188:191], v[204:207], v[96:99]
	v_mfma_i32_16x16x64_i8 v[84:87], v[180:183], v[212:215], v[84:87]
	v_mfma_i32_16x16x64_i8 v[80:83], v[188:191], v[212:215], v[80:83]
	v_mfma_i32_16x16x64_i8 v[68:71], v[180:183], v[220:223], v[68:71]
	v_mfma_i32_16x16x64_i8 v[64:67], v[188:191], v[220:223], v[64:67]
	s_barrier
	ds_read_b128 v[192:195], v165 offset:49152
	ds_read_b128 v[196:199], v165 offset:50176
	ds_read_b128 v[200:203], v165 offset:51200
	ds_read_b128 v[204:207], v165 offset:52224
	ds_read_b128 v[208:211], v165 offset:53248
	ds_read_b128 v[212:215], v165 offset:54272
	ds_read_b128 v[216:219], v165 offset:55296
	ds_read_b128 v[220:223], v165 offset:56320
	s_mov_b32 m0, s28
	s_nop 0
	global_load_lds_dwordx4 v132, s[98:99]
	s_add_i32 m0, s28, 0x2000
	s_add_i32 s28, s56, s35
	global_load_lds_dwordx4 v128, s[98:99]
	s_mov_b32 m0, s28
	s_nop 0
	global_load_lds_dwordx4 v132, s[6:7]
	s_add_i32 m0, s28, 0x2000
	s_nop 0
	global_load_lds_dwordx4 v128, s[6:7]
	s_mov_b32 m0, s43
	s_nop 0
	global_load_lds_dwordx4 v134, s[100:101]
	s_mov_b32 m0, s44
	s_nop 0
	global_load_lds_dwordx4 v130, s[100:101]
	s_waitcnt vmcnt(8)
	s_waitcnt lgkmcnt(0)
	s_barrier
	s_waitcnt lgkmcnt(0)
	v_mfma_i32_16x16x64_i8 v[60:63], v[144:147], v[192:195], v[60:63]
	v_mfma_i32_16x16x64_i8 v[56:59], v[168:171], v[192:195], v[56:59]
	v_mfma_i32_16x16x64_i8 v[44:47], v[144:147], v[200:203], v[44:47]
	v_mfma_i32_16x16x64_i8 v[40:43], v[168:171], v[200:203], v[40:43]
	v_mfma_i32_16x16x64_i8 v[28:31], v[144:147], v[208:211], v[28:31]
	v_mfma_i32_16x16x64_i8 v[24:27], v[168:171], v[208:211], v[24:27]
	v_mfma_i32_16x16x64_i8 v[12:15], v[144:147], v[216:219], v[12:15]
	v_mfma_i32_16x16x64_i8 v[8:11], v[168:171], v[216:219], v[8:11]
	v_mfma_i32_16x16x64_i8 v[60:63], v[148:151], v[196:199], v[60:63]
	v_mfma_i32_16x16x64_i8 v[56:59], v[172:175], v[196:199], v[56:59]
	v_mfma_i32_16x16x64_i8 v[44:47], v[148:151], v[204:207], v[44:47]
	v_mfma_i32_16x16x64_i8 v[40:43], v[172:175], v[204:207], v[40:43]
	v_mfma_i32_16x16x64_i8 v[28:31], v[148:151], v[212:215], v[28:31]
	v_mfma_i32_16x16x64_i8 v[24:27], v[172:175], v[212:215], v[24:27]
	v_mfma_i32_16x16x64_i8 v[12:15], v[148:151], v[220:223], v[12:15]
	v_mfma_i32_16x16x64_i8 v[8:11], v[172:175], v[220:223], v[8:11]
	v_mfma_i32_16x16x64_i8 v[52:55], v[176:179], v[192:195], v[52:55]
	v_mfma_i32_16x16x64_i8 v[48:51], v[184:187], v[192:195], v[48:51]
	v_mfma_i32_16x16x64_i8 v[36:39], v[176:179], v[200:203], v[36:39]
	v_mfma_i32_16x16x64_i8 v[32:35], v[184:187], v[200:203], v[32:35]
	v_mfma_i32_16x16x64_i8 v[20:23], v[176:179], v[208:211], v[20:23]
	v_mfma_i32_16x16x64_i8 v[16:19], v[184:187], v[208:211], v[16:19]
	v_mfma_i32_16x16x64_i8 v[4:7], v[176:179], v[216:219], v[4:7]
	v_mfma_i32_16x16x64_i8 v[0:3], v[184:187], v[216:219], v[0:3]
	v_mfma_i32_16x16x64_i8 v[52:55], v[180:183], v[196:199], v[52:55]
	v_mfma_i32_16x16x64_i8 v[48:51], v[188:191], v[196:199], v[48:51]
	v_mfma_i32_16x16x64_i8 v[36:39], v[180:183], v[204:207], v[36:39]
	v_mfma_i32_16x16x64_i8 v[32:35], v[188:191], v[204:207], v[32:35]
	v_mfma_i32_16x16x64_i8 v[20:23], v[180:183], v[212:215], v[20:23]
	v_mfma_i32_16x16x64_i8 v[16:19], v[188:191], v[212:215], v[16:19]
	v_mfma_i32_16x16x64_i8 v[4:7], v[180:183], v[220:223], v[4:7]
	v_mfma_i32_16x16x64_i8 v[0:3], v[188:191], v[220:223], v[0:3]
	s_barrier
	s_add_i32 s54, s54, 2
	s_add_u32 s52, s52, 0x100
	s_addc_u32 s53, s53, 0
	s_add_u32 s4, s4, 0x100
	s_addc_u32 s5, s5, 0
	s_cmp_gt_u32 s54, 29
	s_cbranch_scc0 .LBB0_726
	s_setprio 0
	s_and_b64 vcc, exec, s[18:19]
	s_cbranch_vccz .LBB0_729
	s_barrier

.Lsp_skip8:
.LBB0_1356:
	ds_read_b128 v[144:147], v180
	ds_read_b128 v[148:151], v180 offset:1024
	ds_read_b128 v[152:155], v180 offset:2048
	ds_read_b128 v[156:159], v180 offset:3072
	ds_read_b128 v[160:163], v181
	ds_read_b128 v[164:167], v181 offset:1024
	ds_read_b128 v[168:171], v181 offset:2048
	ds_read_b128 v[172:175], v181 offset:3072
	ds_read_b128 v[186:189], v182
	ds_read_b128 v[190:193], v182 offset:1024
	ds_read_b128 v[194:197], v182 offset:2048
	ds_read_b128 v[198:201], v182 offset:3072
	ds_read_b128 v[202:205], v182 offset:4096
	ds_read_b128 v[206:209], v182 offset:5120
	ds_read_b128 v[210:213], v182 offset:6144
	ds_read_b128 v[214:217], v182 offset:7168
	s_add_u32 s34, s30, 0xfff80080
	s_addc_u32 s35, s31, -1
	s_cmp_eq_u32 s58, 28
	s_cselect_b32 s37, s1, s35
	s_cselect_b32 s36, s23, s34
	s_cselect_b32 s35, s21, s57
	s_cselect_b32 s34, s29, s33
	s_add_i32 m0, s43, 0xc000
	s_nop 0
	global_load_lds_dwordx4 v138, s[30:31]
	s_add_i32 m0, s43, 0xe000
	s_nop 0
	global_load_lds_dwordx4 v136, s[30:31]
	s_waitcnt vmcnt(8)
	s_waitcnt lgkmcnt(0)
	s_barrier
	s_waitcnt lgkmcnt(0)
	v_mfma_i32_16x16x64_i8 v[124:127], v[144:147], v[186:189], v[124:127]
	v_mfma_i32_16x16x64_i8 v[120:123], v[152:155], v[186:189], v[120:123]
	v_mfma_i32_16x16x64_i8 v[108:111], v[144:147], v[194:197], v[108:111]
	v_mfma_i32_16x16x64_i8 v[104:107], v[152:155], v[194:197], v[104:107]
	s_add_u32 s98, s34, s16
	s_addc_u32 s99, s35, s17
	s_add_i32 s59, s52, s42
	v_mfma_i32_16x16x64_i8 v[92:95], v[144:147], v[202:205], v[92:95]
	s_add_u32 s100, s36, s16
	s_addc_u32 s101, s37, s17
	v_mfma_i32_16x16x64_i8 v[88:91], v[152:155], v[202:205], v[88:91]
	v_mfma_i32_16x16x64_i8 v[76:79], v[144:147], v[210:213], v[76:79]
	v_mfma_i32_16x16x64_i8 v[72:75], v[152:155], v[210:213], v[72:75]
	s_add_u32 s60, s34, 0x80000
	v_mfma_i32_16x16x64_i8 v[124:127], v[148:151], v[190:193], v[124:127]
	v_mfma_i32_16x16x64_i8 v[120:123], v[156:159], v[190:193], v[120:123]
	v_mfma_i32_16x16x64_i8 v[108:111], v[148:151], v[198:201], v[108:111]
	v_mfma_i32_16x16x64_i8 v[104:107], v[156:159], v[198:201], v[104:107]
	s_addc_u32 s61, s35, 0
	v_mfma_i32_16x16x64_i8 v[92:95], v[148:151], v[206:209], v[92:95]
	v_mfma_i32_16x16x64_i8 v[88:91], v[156:159], v[206:209], v[88:91]
	v_mfma_i32_16x16x64_i8 v[76:79], v[148:151], v[214:217], v[76:79]
	v_mfma_i32_16x16x64_i8 v[72:75], v[156:159], v[214:217], v[72:75]
	v_mfma_i32_16x16x64_i8 v[116:119], v[160:163], v[186:189], v[116:119]
	v_mfma_i32_16x16x64_i8 v[112:115], v[168:171], v[186:189], v[112:115]
	v_mfma_i32_16x16x64_i8 v[100:103], v[160:163], v[194:197], v[100:103]
	v_mfma_i32_16x16x64_i8 v[96:99], v[168:171], v[194:197], v[96:99]
	v_mfma_i32_16x16x64_i8 v[84:87], v[160:163], v[202:205], v[84:87]
	v_mfma_i32_16x16x64_i8 v[80:83], v[168:171], v[202:205], v[80:83]
	v_mfma_i32_16x16x64_i8 v[68:71], v[160:163], v[210:213], v[68:71]
	v_mfma_i32_16x16x64_i8 v[64:67], v[168:171], v[210:213], v[64:67]
	v_mfma_i32_16x16x64_i8 v[116:119], v[164:167], v[190:193], v[116:119]
	v_mfma_i32_16x16x64_i8 v[112:115], v[172:175], v[190:193], v[112:115]
	v_mfma_i32_16x16x64_i8 v[100:103], v[164:167], v[198:201], v[100:103]
	v_mfma_i32_16x16x64_i8 v[96:99], v[172:175], v[198:201], v[96:99]
	v_mfma_i32_16x16x64_i8 v[84:87], v[164:167], v[206:209], v[84:87]
	v_mfma_i32_16x16x64_i8 v[80:83], v[172:175], v[206:209], v[80:83]
	v_mfma_i32_16x16x64_i8 v[68:71], v[164:167], v[214:217], v[68:71]
	v_mfma_i32_16x16x64_i8 v[64:67], v[172:175], v[214:217], v[64:67]
	s_barrier
	ds_read_b128 v[186:189], v182 offset:16384
	ds_read_b128 v[190:193], v182 offset:17408
	ds_read_b128 v[194:197], v182 offset:18432
	ds_read_b128 v[198:201], v182 offset:19456
	ds_read_b128 v[202:205], v182 offset:20480
	ds_read_b128 v[206:209], v182 offset:21504
	ds_read_b128 v[210:213], v182 offset:22528
	ds_read_b128 v[214:217], v182 offset:23552
	s_mov_b32 m0, s59
	s_nop 0
	global_load_lds_dwordx4 v130, s[34:35]
	s_add_i32 m0, s59, 0x2000
	s_add_i32 s59, s53, s42
	global_load_lds_dwordx4 v134, s[34:35]
	s_mov_b32 m0, s59
	s_nop 0
	global_load_lds_dwordx4 v130, s[60:61]
	s_add_i32 m0, s59, 0x2000
	s_nop 0
	global_load_lds_dwordx4 v134, s[60:61]
	s_mov_b32 m0, s43
	s_nop 0
	global_load_lds_dwordx4 v128, s[36:37]
	s_mov_b32 m0, s44
	s_nop 0
	global_load_lds_dwordx4 v132, s[36:37]
	s_waitcnt vmcnt(8)
	s_waitcnt lgkmcnt(0)
	s_barrier
	s_waitcnt lgkmcnt(0)
	v_mfma_i32_16x16x64_i8 v[60:63], v[144:147], v[186:189], v[60:63]
	v_mfma_i32_16x16x64_i8 v[56:59], v[152:155], v[186:189], v[56:59]
	v_mfma_i32_16x16x64_i8 v[44:47], v[144:147], v[194:197], v[44:47]
	v_mfma_i32_16x16x64_i8 v[40:43], v[152:155], v[194:197], v[40:43]
	s_add_i32 s59, 0, 0x18000
	v_mfma_i32_16x16x64_i8 v[28:31], v[144:147], v[202:205], v[28:31]
	v_mfma_i32_16x16x64_i8 v[24:27], v[152:155], v[202:205], v[24:27]
	s_add_i32 s60, 0, 0x1c000
	v_mfma_i32_16x16x64_i8 v[12:15], v[144:147], v[210:213], v[12:15]
	v_mfma_i32_16x16x64_i8 v[8:11], v[152:155], v[210:213], v[8:11]
	s_add_u32 s36, s36, 0x80000
	v_mfma_i32_16x16x64_i8 v[60:63], v[148:151], v[190:193], v[60:63]
	v_mfma_i32_16x16x64_i8 v[56:59], v[156:159], v[190:193], v[56:59]
	s_addc_u32 s37, s37, 0
	v_mfma_i32_16x16x64_i8 v[44:47], v[148:151], v[198:201], v[44:47]
	v_mfma_i32_16x16x64_i8 v[40:43], v[156:159], v[198:201], v[40:43]
	v_mfma_i32_16x16x64_i8 v[28:31], v[148:151], v[206:209], v[28:31]
	v_mfma_i32_16x16x64_i8 v[24:27], v[156:159], v[206:209], v[24:27]
	v_mfma_i32_16x16x64_i8 v[12:15], v[148:151], v[214:217], v[12:15]
	v_mfma_i32_16x16x64_i8 v[8:11], v[156:159], v[214:217], v[8:11]
	v_mfma_i32_16x16x64_i8 v[52:55], v[160:163], v[186:189], v[52:55]
	v_mfma_i32_16x16x64_i8 v[48:51], v[168:171], v[186:189], v[48:51]
	v_mfma_i32_16x16x64_i8 v[36:39], v[160:163], v[194:197], v[36:39]
	v_mfma_i32_16x16x64_i8 v[32:35], v[168:171], v[194:197], v[32:35]
	v_mfma_i32_16x16x64_i8 v[20:23], v[160:163], v[202:205], v[20:23]
	v_mfma_i32_16x16x64_i8 v[16:19], v[168:171], v[202:205], v[16:19]
	v_mfma_i32_16x16x64_i8 v[4:7], v[160:163], v[210:213], v[4:7]
	v_mfma_i32_16x16x64_i8 v[0:3], v[168:171], v[210:213], v[0:3]
	v_mfma_i32_16x16x64_i8 v[52:55], v[164:167], v[190:193], v[52:55]
	v_mfma_i32_16x16x64_i8 v[48:51], v[172:175], v[190:193], v[48:51]
	v_mfma_i32_16x16x64_i8 v[36:39], v[164:167], v[198:201], v[36:39]
	v_mfma_i32_16x16x64_i8 v[32:35], v[172:175], v[198:201], v[32:35]
	v_mfma_i32_16x16x64_i8 v[20:23], v[164:167], v[206:209], v[20:23]
	v_mfma_i32_16x16x64_i8 v[16:19], v[172:175], v[206:209], v[16:19]
	v_mfma_i32_16x16x64_i8 v[4:7], v[164:167], v[214:217], v[4:7]
	v_mfma_i32_16x16x64_i8 v[0:3], v[172:175], v[214:217], v[0:3]
	s_barrier
	ds_read_b128 v[186:189], v182 offset:32768
	ds_read_b128 v[190:193], v182 offset:33792
	ds_read_b128 v[194:197], v182 offset:34816
	ds_read_b128 v[198:201], v182 offset:35840
	ds_read_b128 v[202:205], v182 offset:36864
	ds_read_b128 v[206:209], v182 offset:37888
	ds_read_b128 v[210:213], v182 offset:38912
	ds_read_b128 v[214:217], v182 offset:39936
	v_add_u32_e32 v156, s59, v178
	v_add_u32_e32 v172, s60, v178
	ds_read_b128 v[144:147], v156
	ds_read_b128 v[148:151], v156 offset:1024
	ds_read_b128 v[152:155], v156 offset:2048
	ds_read_b128 v[156:159], v156 offset:3072
	ds_read_b128 v[160:163], v172
	ds_read_b128 v[164:167], v172 offset:1024
	ds_read_b128 v[168:171], v172 offset:2048
	ds_read_b128 v[172:175], v172 offset:3072
	s_mov_b32 m0, s45
	s_nop 0
	global_load_lds_dwordx4 v128, s[36:37]
	s_mov_b32 m0, s46
	s_nop 0
	global_load_lds_dwordx4 v132, s[36:37]
	s_waitcnt vmcnt(8)
	s_waitcnt lgkmcnt(0)
	s_barrier
	s_waitcnt lgkmcnt(0)
	v_mfma_i32_16x16x64_i8 v[124:127], v[144:147], v[186:189], v[124:127]
	v_mfma_i32_16x16x64_i8 v[120:123], v[152:155], v[186:189], v[120:123]
	v_mfma_i32_16x16x64_i8 v[108:111], v[144:147], v[194:197], v[108:111]
	v_mfma_i32_16x16x64_i8 v[104:107], v[152:155], v[194:197], v[104:107]
	s_add_i32 s36, s59, s42
	v_mfma_i32_16x16x64_i8 v[92:95], v[144:147], v[202:205], v[92:95]
	v_mfma_i32_16x16x64_i8 v[88:91], v[152:155], v[202:205], v[88:91]
	v_mfma_i32_16x16x64_i8 v[76:79], v[144:147], v[210:213], v[76:79]
	v_mfma_i32_16x16x64_i8 v[72:75], v[152:155], v[210:213], v[72:75]
	s_add_u32 s34, s34, 0x80080
	v_mfma_i32_16x16x64_i8 v[124:127], v[148:151], v[190:193], v[124:127]
	v_mfma_i32_16x16x64_i8 v[120:123], v[156:159], v[190:193], v[120:123]
	v_mfma_i32_16x16x64_i8 v[108:111], v[148:151], v[198:201], v[108:111]
	v_mfma_i32_16x16x64_i8 v[104:107], v[156:159], v[198:201], v[104:107]
	s_addc_u32 s35, s35, 0
	v_mfma_i32_16x16x64_i8 v[92:95], v[148:151], v[206:209], v[92:95]
	v_mfma_i32_16x16x64_i8 v[88:91], v[156:159], v[206:209], v[88:91]
	v_mfma_i32_16x16x64_i8 v[76:79], v[148:151], v[214:217], v[76:79]
	v_mfma_i32_16x16x64_i8 v[72:75], v[156:159], v[214:217], v[72:75]
	v_mfma_i32_16x16x64_i8 v[116:119], v[160:163], v[186:189], v[116:119]
	v_mfma_i32_16x16x64_i8 v[112:115], v[168:171], v[186:189], v[112:115]
	v_mfma_i32_16x16x64_i8 v[100:103], v[160:163], v[194:197], v[100:103]
	v_mfma_i32_16x16x64_i8 v[96:99], v[168:171], v[194:197], v[96:99]
	v_mfma_i32_16x16x64_i8 v[84:87], v[160:163], v[202:205], v[84:87]
	v_mfma_i32_16x16x64_i8 v[80:83], v[168:171], v[202:205], v[80:83]
	v_mfma_i32_16x16x64_i8 v[68:71], v[160:163], v[210:213], v[68:71]
	v_mfma_i32_16x16x64_i8 v[64:67], v[168:171], v[210:213], v[64:67]
	v_mfma_i32_16x16x64_i8 v[116:119], v[164:167], v[190:193], v[116:119]
	v_mfma_i32_16x16x64_i8 v[112:115], v[172:175], v[190:193], v[112:115]
	v_mfma_i32_16x16x64_i8 v[100:103], v[164:167], v[198:201], v[100:103]
	v_mfma_i32_16x16x64_i8 v[96:99], v[172:175], v[198:201], v[96:99]
	v_mfma_i32_16x16x64_i8 v[84:87], v[164:167], v[206:209], v[84:87]
	v_mfma_i32_16x16x64_i8 v[80:83], v[172:175], v[206:209], v[80:83]
	v_mfma_i32_16x16x64_i8 v[68:71], v[164:167], v[214:217], v[68:71]
	v_mfma_i32_16x16x64_i8 v[64:67], v[172:175], v[214:217], v[64:67]
	s_barrier
	ds_read_b128 v[186:189], v182 offset:49152
	ds_read_b128 v[190:193], v182 offset:50176
	ds_read_b128 v[194:197], v182 offset:51200
	ds_read_b128 v[198:201], v182 offset:52224
	ds_read_b128 v[202:205], v182 offset:53248
	ds_read_b128 v[206:209], v182 offset:54272
	ds_read_b128 v[210:213], v182 offset:55296
	ds_read_b128 v[214:217], v182 offset:56320
	s_mov_b32 m0, s36
	s_nop 0
	global_load_lds_dwordx4 v130, s[98:99]
	s_add_i32 m0, s36, 0x2000
	s_add_i32 s36, s60, s42
	global_load_lds_dwordx4 v134, s[98:99]
	s_mov_b32 m0, s36
	s_nop 0
	global_load_lds_dwordx4 v130, s[34:35]
	s_add_i32 m0, s36, 0x2000
	s_nop 0
	global_load_lds_dwordx4 v134, s[34:35]
	s_mov_b32 m0, s48
	s_nop 0
	global_load_lds_dwordx4 v128, s[100:101]
	s_mov_b32 m0, s49
	s_nop 0
	global_load_lds_dwordx4 v132, s[100:101]
	s_waitcnt vmcnt(8)
	s_waitcnt lgkmcnt(0)
	s_barrier
	s_waitcnt lgkmcnt(0)
	v_mfma_i32_16x16x64_i8 v[60:63], v[144:147], v[186:189], v[60:63]
	v_mfma_i32_16x16x64_i8 v[56:59], v[152:155], v[186:189], v[56:59]
	v_mfma_i32_16x16x64_i8 v[44:47], v[144:147], v[194:197], v[44:47]
	v_mfma_i32_16x16x64_i8 v[40:43], v[152:155], v[194:197], v[40:43]
	v_mfma_i32_16x16x64_i8 v[28:31], v[144:147], v[202:205], v[28:31]
	v_mfma_i32_16x16x64_i8 v[24:27], v[152:155], v[202:205], v[24:27]
	v_mfma_i32_16x16x64_i8 v[12:15], v[144:147], v[210:213], v[12:15]
	v_mfma_i32_16x16x64_i8 v[8:11], v[152:155], v[210:213], v[8:11]
	v_mfma_i32_16x16x64_i8 v[60:63], v[148:151], v[190:193], v[60:63]
	v_mfma_i32_16x16x64_i8 v[56:59], v[156:159], v[190:193], v[56:59]
	v_mfma_i32_16x16x64_i8 v[44:47], v[148:151], v[198:201], v[44:47]
	v_mfma_i32_16x16x64_i8 v[40:43], v[156:159], v[198:201], v[40:43]
	v_mfma_i32_16x16x64_i8 v[28:31], v[148:151], v[206:209], v[28:31]
	v_mfma_i32_16x16x64_i8 v[24:27], v[156:159], v[206:209], v[24:27]
	v_mfma_i32_16x16x64_i8 v[12:15], v[148:151], v[214:217], v[12:15]
	v_mfma_i32_16x16x64_i8 v[8:11], v[156:159], v[214:217], v[8:11]
	v_mfma_i32_16x16x64_i8 v[52:55], v[160:163], v[186:189], v[52:55]
	v_mfma_i32_16x16x64_i8 v[48:51], v[168:171], v[186:189], v[48:51]
	v_mfma_i32_16x16x64_i8 v[36:39], v[160:163], v[194:197], v[36:39]
	v_mfma_i32_16x16x64_i8 v[32:35], v[168:171], v[194:197], v[32:35]
	v_mfma_i32_16x16x64_i8 v[20:23], v[160:163], v[202:205], v[20:23]
	v_mfma_i32_16x16x64_i8 v[16:19], v[168:171], v[202:205], v[16:19]
	v_mfma_i32_16x16x64_i8 v[4:7], v[160:163], v[210:213], v[4:7]
	v_mfma_i32_16x16x64_i8 v[0:3], v[168:171], v[210:213], v[0:3]
	v_mfma_i32_16x16x64_i8 v[52:55], v[164:167], v[190:193], v[52:55]
	v_mfma_i32_16x16x64_i8 v[48:51], v[172:175], v[190:193], v[48:51]
	v_mfma_i32_16x16x64_i8 v[36:39], v[164:167], v[198:201], v[36:39]
	v_mfma_i32_16x16x64_i8 v[32:35], v[172:175], v[198:201], v[32:35]
	v_mfma_i32_16x16x64_i8 v[20:23], v[164:167], v[206:209], v[20:23]
	v_mfma_i32_16x16x64_i8 v[16:19], v[172:175], v[206:209], v[16:19]
	v_mfma_i32_16x16x64_i8 v[4:7], v[164:167], v[214:217], v[4:7]
	v_mfma_i32_16x16x64_i8 v[0:3], v[172:175], v[214:217], v[0:3]
	s_barrier
	s_add_i32 s58, s58, 2
	s_add_u32 s33, s33, 0x100
	s_addc_u32 s57, s57, 0
	s_add_u32 s30, s30, 0x100
	s_addc_u32 s31, s31, 0
	s_cmp_gt_u32 s58, 29
	s_cbranch_scc0 .LBB0_1356
	s_setprio 0
	s_and_b64 vcc, exec, s[18:19]
	s_cbranch_vccz .LBB0_1359
	s_barrier

.Lsp_skip9:
.LBB0_1841:
	ds_read_b128 v[186:189], v183
	ds_read_b128 v[190:193], v183 offset:1024
	ds_read_b128 v[194:197], v183 offset:2048
	ds_read_b128 v[198:201], v183 offset:3072
	ds_read_b128 v[202:205], v183 offset:4096
	ds_read_b128 v[206:209], v183 offset:5120
	ds_read_b128 v[210:213], v183 offset:6144
	ds_read_b128 v[214:217], v183 offset:7168
	v_add_u32_e32 v140, s47, v181
	v_add_u32_e32 v174, s48, v181
	ds_read_b128 v[124:127], v140
	ds_read_b128 v[132:135], v140 offset:1024
	ds_read_b128 v[136:139], v140 offset:2048
	ds_read_b128 v[140:143], v140 offset:3072
	ds_read_b128 v[162:165], v174
	ds_read_b128 v[166:169], v174 offset:1024
	ds_read_b128 v[170:173], v174 offset:2048
	ds_read_b128 v[174:177], v174 offset:3072
	s_add_u32 s30, s28, 0xffe00080
	s_addc_u32 s31, s29, -1
	s_cmpk_eq_i32 s53, 0x7c
	s_cselect_b32 s35, s19, s31
	s_cselect_b32 s34, s25, s30
	s_cselect_b32 s31, s17, s52
	s_cselect_b32 s30, s50, s51
	s_add_i32 m0, s27, 0xc000
	s_nop 0
	global_load_lds_dwordx4 v156, s[28:29]
	s_add_i32 m0, s27, 0xe000
	s_nop 0
	global_load_lds_dwordx4 v154, s[28:29]
	s_waitcnt vmcnt(8)
	s_waitcnt lgkmcnt(0)
	s_barrier
	s_waitcnt lgkmcnt(0)
	v_mfma_i32_16x16x64_i8 v[116:119], v[124:127], v[186:189], v[116:119]
	v_mfma_i32_16x16x64_i8 v[104:107], v[136:139], v[186:189], v[104:107]
	v_mfma_i32_16x16x64_i8 v[112:115], v[124:127], v[194:197], v[112:115]
	v_mfma_i32_16x16x64_i8 v[108:111], v[136:139], v[194:197], v[108:111]
	s_add_u32 s98, s30, s10
	s_addc_u32 s99, s31, s11
	s_add_i32 s54, s47, s38
	v_mfma_i32_16x16x64_i8 v[92:95], v[124:127], v[202:205], v[92:95]
	s_add_u32 s100, s34, s10
	s_addc_u32 s101, s35, s11
	v_mfma_i32_16x16x64_i8 v[88:91], v[136:139], v[202:205], v[88:91]
	v_mfma_i32_16x16x64_i8 v[76:79], v[124:127], v[210:213], v[76:79]
	v_mfma_i32_16x16x64_i8 v[72:75], v[136:139], v[210:213], v[72:75]
	v_mfma_i32_16x16x64_i8 v[116:119], v[132:135], v[190:193], v[116:119]
	v_mfma_i32_16x16x64_i8 v[104:107], v[140:143], v[190:193], v[104:107]
	s_add_i32 s56, s48, s38
	v_mfma_i32_16x16x64_i8 v[112:115], v[132:135], v[198:201], v[112:115]
	v_mfma_i32_16x16x64_i8 v[108:111], v[140:143], v[198:201], v[108:111]
	v_mfma_i32_16x16x64_i8 v[92:95], v[132:135], v[206:209], v[92:95]
	v_mfma_i32_16x16x64_i8 v[88:91], v[140:143], v[206:209], v[88:91]
	v_mfma_i32_16x16x64_i8 v[76:79], v[132:135], v[214:217], v[76:79]
	v_mfma_i32_16x16x64_i8 v[72:75], v[140:143], v[214:217], v[72:75]
	v_mfma_i32_16x16x64_i8 v[128:131], v[162:165], v[186:189], v[128:131]
	v_mfma_i32_16x16x64_i8 v[120:123], v[170:173], v[186:189], v[120:123]
	v_mfma_i32_16x16x64_i8 v[100:103], v[162:165], v[194:197], v[100:103]
	v_mfma_i32_16x16x64_i8 v[96:99], v[170:173], v[194:197], v[96:99]
	v_mfma_i32_16x16x64_i8 v[84:87], v[162:165], v[202:205], v[84:87]
	v_mfma_i32_16x16x64_i8 v[80:83], v[170:173], v[202:205], v[80:83]
	v_mfma_i32_16x16x64_i8 v[68:71], v[162:165], v[210:213], v[68:71]
	v_mfma_i32_16x16x64_i8 v[64:67], v[170:173], v[210:213], v[64:67]
	v_mfma_i32_16x16x64_i8 v[128:131], v[166:169], v[190:193], v[128:131]
	v_mfma_i32_16x16x64_i8 v[120:123], v[174:177], v[190:193], v[120:123]
	v_mfma_i32_16x16x64_i8 v[100:103], v[166:169], v[198:201], v[100:103]
	v_mfma_i32_16x16x64_i8 v[96:99], v[174:177], v[198:201], v[96:99]
	v_mfma_i32_16x16x64_i8 v[84:87], v[166:169], v[206:209], v[84:87]
	v_mfma_i32_16x16x64_i8 v[80:83], v[174:177], v[206:209], v[80:83]
	v_mfma_i32_16x16x64_i8 v[68:71], v[166:169], v[214:217], v[68:71]
	v_mfma_i32_16x16x64_i8 v[64:67], v[174:177], v[214:217], v[64:67]
	s_barrier
	ds_read_b128 v[186:189], v183 offset:16384
	ds_read_b128 v[190:193], v183 offset:17408
	ds_read_b128 v[194:197], v183 offset:18432
	ds_read_b128 v[198:201], v183 offset:19456
	ds_read_b128 v[202:205], v183 offset:20480
	ds_read_b128 v[206:209], v183 offset:21504
	ds_read_b128 v[210:213], v183 offset:22528
	ds_read_b128 v[214:217], v183 offset:23552
	s_mov_b32 m0, s54
	s_nop 0
	global_load_lds_dwordx4 v146, s[30:31]
	s_add_i32 m0, s54, 0x2000
	s_add_u32 s54, s30, 0x200000
	s_addc_u32 s55, s31, 0
	global_load_lds_dwordx4 v150, s[30:31]
	s_mov_b32 m0, s56
	s_nop 0
	global_load_lds_dwordx4 v146, s[54:55]
	s_add_i32 m0, s56, 0x2000
	s_nop 0
	global_load_lds_dwordx4 v150, s[54:55]
	s_mov_b32 m0, s27
	s_nop 0
	global_load_lds_dwordx4 v144, s[34:35]
	s_mov_b32 m0, s39
	s_nop 0
	global_load_lds_dwordx4 v148, s[34:35]
	s_waitcnt vmcnt(8)
	s_waitcnt lgkmcnt(0)
	s_barrier
	s_waitcnt lgkmcnt(0)
	v_mfma_i32_16x16x64_i8 v[60:63], v[124:127], v[186:189], v[60:63]
	v_mfma_i32_16x16x64_i8 v[56:59], v[136:139], v[186:189], v[56:59]
	v_mfma_i32_16x16x64_i8 v[44:47], v[124:127], v[194:197], v[44:47]
	v_mfma_i32_16x16x64_i8 v[40:43], v[136:139], v[194:197], v[40:43]
	s_add_i32 s54, 0, 0x18000
	v_mfma_i32_16x16x64_i8 v[28:31], v[124:127], v[202:205], v[28:31]
	v_mfma_i32_16x16x64_i8 v[24:27], v[136:139], v[202:205], v[24:27]
	s_add_i32 s55, 0, 0x1c000
	v_mfma_i32_16x16x64_i8 v[12:15], v[124:127], v[210:213], v[12:15]
	v_mfma_i32_16x16x64_i8 v[8:11], v[136:139], v[210:213], v[8:11]
	s_add_u32 s34, s34, 0x200000
	v_mfma_i32_16x16x64_i8 v[60:63], v[132:135], v[190:193], v[60:63]
	v_mfma_i32_16x16x64_i8 v[56:59], v[140:143], v[190:193], v[56:59]
	s_addc_u32 s35, s35, 0
	v_mfma_i32_16x16x64_i8 v[44:47], v[132:135], v[198:201], v[44:47]
	v_mfma_i32_16x16x64_i8 v[40:43], v[140:143], v[198:201], v[40:43]
	v_mfma_i32_16x16x64_i8 v[28:31], v[132:135], v[206:209], v[28:31]
	v_mfma_i32_16x16x64_i8 v[24:27], v[140:143], v[206:209], v[24:27]
	v_mfma_i32_16x16x64_i8 v[12:15], v[132:135], v[214:217], v[12:15]
	v_mfma_i32_16x16x64_i8 v[8:11], v[140:143], v[214:217], v[8:11]
	v_mfma_i32_16x16x64_i8 v[52:55], v[162:165], v[186:189], v[52:55]
	v_mfma_i32_16x16x64_i8 v[48:51], v[170:173], v[186:189], v[48:51]
	v_mfma_i32_16x16x64_i8 v[36:39], v[162:165], v[194:197], v[36:39]
	v_mfma_i32_16x16x64_i8 v[32:35], v[170:173], v[194:197], v[32:35]
	v_mfma_i32_16x16x64_i8 v[20:23], v[162:165], v[202:205], v[20:23]
	v_mfma_i32_16x16x64_i8 v[16:19], v[170:173], v[202:205], v[16:19]
	v_mfma_i32_16x16x64_i8 v[4:7], v[162:165], v[210:213], v[4:7]
	v_mfma_i32_16x16x64_i8 v[0:3], v[170:173], v[210:213], v[0:3]
	v_mfma_i32_16x16x64_i8 v[52:55], v[166:169], v[190:193], v[52:55]
	v_mfma_i32_16x16x64_i8 v[48:51], v[174:177], v[190:193], v[48:51]
	v_mfma_i32_16x16x64_i8 v[36:39], v[166:169], v[198:201], v[36:39]
	v_mfma_i32_16x16x64_i8 v[32:35], v[174:177], v[198:201], v[32:35]
	v_mfma_i32_16x16x64_i8 v[20:23], v[166:169], v[206:209], v[20:23]
	v_mfma_i32_16x16x64_i8 v[16:19], v[174:177], v[206:209], v[16:19]
	v_mfma_i32_16x16x64_i8 v[4:7], v[166:169], v[214:217], v[4:7]
	v_mfma_i32_16x16x64_i8 v[0:3], v[174:177], v[214:217], v[0:3]
	s_barrier
	ds_read_b128 v[186:189], v183 offset:32768
	ds_read_b128 v[190:193], v183 offset:33792
	ds_read_b128 v[194:197], v183 offset:34816
	ds_read_b128 v[198:201], v183 offset:35840
	ds_read_b128 v[202:205], v183 offset:36864
	ds_read_b128 v[206:209], v183 offset:37888
	ds_read_b128 v[210:213], v183 offset:38912
	ds_read_b128 v[214:217], v183 offset:39936
	v_add_u32_e32 v140, s54, v181
	v_add_u32_e32 v174, s55, v181
	ds_read_b128 v[124:127], v140
	ds_read_b128 v[132:135], v140 offset:1024
	ds_read_b128 v[136:139], v140 offset:2048
	ds_read_b128 v[140:143], v140 offset:3072
	ds_read_b128 v[162:165], v174
	ds_read_b128 v[166:169], v174 offset:1024
	ds_read_b128 v[170:173], v174 offset:2048
	ds_read_b128 v[174:177], v174 offset:3072
	s_mov_b32 m0, s40
	s_nop 0
	global_load_lds_dwordx4 v144, s[34:35]
	s_mov_b32 m0, s41
	s_nop 0
	global_load_lds_dwordx4 v148, s[34:35]
	s_waitcnt vmcnt(8)
	s_waitcnt lgkmcnt(0)
	s_barrier
	s_waitcnt lgkmcnt(0)
	v_mfma_i32_16x16x64_i8 v[116:119], v[124:127], v[186:189], v[116:119]
	v_mfma_i32_16x16x64_i8 v[104:107], v[136:139], v[186:189], v[104:107]
	v_mfma_i32_16x16x64_i8 v[112:115], v[124:127], v[194:197], v[112:115]
	v_mfma_i32_16x16x64_i8 v[108:111], v[136:139], v[194:197], v[108:111]
	s_add_i32 s34, s54, s38
	v_mfma_i32_16x16x64_i8 v[92:95], v[124:127], v[202:205], v[92:95]
	v_mfma_i32_16x16x64_i8 v[88:91], v[136:139], v[202:205], v[88:91]
	v_mfma_i32_16x16x64_i8 v[76:79], v[124:127], v[210:213], v[76:79]
	v_mfma_i32_16x16x64_i8 v[72:75], v[136:139], v[210:213], v[72:75]
	s_add_u32 s30, s30, 0x200080
	v_mfma_i32_16x16x64_i8 v[116:119], v[132:135], v[190:193], v[116:119]
	v_mfma_i32_16x16x64_i8 v[104:107], v[140:143], v[190:193], v[104:107]
	v_mfma_i32_16x16x64_i8 v[112:115], v[132:135], v[198:201], v[112:115]
	v_mfma_i32_16x16x64_i8 v[108:111], v[140:143], v[198:201], v[108:111]
	s_addc_u32 s31, s31, 0
	v_mfma_i32_16x16x64_i8 v[92:95], v[132:135], v[206:209], v[92:95]
	v_mfma_i32_16x16x64_i8 v[88:91], v[140:143], v[206:209], v[88:91]
	v_mfma_i32_16x16x64_i8 v[76:79], v[132:135], v[214:217], v[76:79]
	v_mfma_i32_16x16x64_i8 v[72:75], v[140:143], v[214:217], v[72:75]
	v_mfma_i32_16x16x64_i8 v[128:131], v[162:165], v[186:189], v[128:131]
	v_mfma_i32_16x16x64_i8 v[120:123], v[170:173], v[186:189], v[120:123]
	v_mfma_i32_16x16x64_i8 v[100:103], v[162:165], v[194:197], v[100:103]
	v_mfma_i32_16x16x64_i8 v[96:99], v[170:173], v[194:197], v[96:99]
	v_mfma_i32_16x16x64_i8 v[84:87], v[162:165], v[202:205], v[84:87]
	v_mfma_i32_16x16x64_i8 v[80:83], v[170:173], v[202:205], v[80:83]
	v_mfma_i32_16x16x64_i8 v[68:71], v[162:165], v[210:213], v[68:71]
	v_mfma_i32_16x16x64_i8 v[64:67], v[170:173], v[210:213], v[64:67]
	v_mfma_i32_16x16x64_i8 v[128:131], v[166:169], v[190:193], v[128:131]
	v_mfma_i32_16x16x64_i8 v[120:123], v[174:177], v[190:193], v[120:123]
	v_mfma_i32_16x16x64_i8 v[100:103], v[166:169], v[198:201], v[100:103]
	v_mfma_i32_16x16x64_i8 v[96:99], v[174:177], v[198:201], v[96:99]
	v_mfma_i32_16x16x64_i8 v[84:87], v[166:169], v[206:209], v[84:87]
	v_mfma_i32_16x16x64_i8 v[80:83], v[174:177], v[206:209], v[80:83]
	v_mfma_i32_16x16x64_i8 v[68:71], v[166:169], v[214:217], v[68:71]
	v_mfma_i32_16x16x64_i8 v[64:67], v[174:177], v[214:217], v[64:67]
	s_barrier
	ds_read_b128 v[186:189], v183 offset:49152
	ds_read_b128 v[190:193], v183 offset:50176
	ds_read_b128 v[194:197], v183 offset:51200
	ds_read_b128 v[198:201], v183 offset:52224
	ds_read_b128 v[202:205], v183 offset:53248
	ds_read_b128 v[206:209], v183 offset:54272
	ds_read_b128 v[210:213], v183 offset:55296
	ds_read_b128 v[214:217], v183 offset:56320
	s_mov_b32 m0, s34
	s_nop 0
	global_load_lds_dwordx4 v146, s[98:99]
	s_add_i32 m0, s34, 0x2000
	s_add_i32 s34, s55, s38
	global_load_lds_dwordx4 v150, s[98:99]
	s_mov_b32 m0, s34
	s_nop 0
	global_load_lds_dwordx4 v146, s[30:31]
	s_add_i32 m0, s34, 0x2000
	s_nop 0
	global_load_lds_dwordx4 v150, s[30:31]
	s_mov_b32 m0, s43
	s_nop 0
	global_load_lds_dwordx4 v144, s[100:101]
	s_mov_b32 m0, s44
	s_nop 0
	global_load_lds_dwordx4 v148, s[100:101]
	s_waitcnt vmcnt(8)
	s_waitcnt lgkmcnt(0)
	s_barrier
	s_waitcnt lgkmcnt(0)
	v_mfma_i32_16x16x64_i8 v[60:63], v[124:127], v[186:189], v[60:63]
	v_mfma_i32_16x16x64_i8 v[56:59], v[136:139], v[186:189], v[56:59]
	v_mfma_i32_16x16x64_i8 v[44:47], v[124:127], v[194:197], v[44:47]
	v_mfma_i32_16x16x64_i8 v[40:43], v[136:139], v[194:197], v[40:43]
	v_mfma_i32_16x16x64_i8 v[28:31], v[124:127], v[202:205], v[28:31]
	v_mfma_i32_16x16x64_i8 v[24:27], v[136:139], v[202:205], v[24:27]
	v_mfma_i32_16x16x64_i8 v[12:15], v[124:127], v[210:213], v[12:15]
	v_mfma_i32_16x16x64_i8 v[8:11], v[136:139], v[210:213], v[8:11]
	v_mfma_i32_16x16x64_i8 v[60:63], v[132:135], v[190:193], v[60:63]
	v_mfma_i32_16x16x64_i8 v[56:59], v[140:143], v[190:193], v[56:59]
	v_mfma_i32_16x16x64_i8 v[44:47], v[132:135], v[198:201], v[44:47]
	v_mfma_i32_16x16x64_i8 v[40:43], v[140:143], v[198:201], v[40:43]
	v_mfma_i32_16x16x64_i8 v[28:31], v[132:135], v[206:209], v[28:31]
	v_mfma_i32_16x16x64_i8 v[24:27], v[140:143], v[206:209], v[24:27]
	v_mfma_i32_16x16x64_i8 v[12:15], v[132:135], v[214:217], v[12:15]
	v_mfma_i32_16x16x64_i8 v[8:11], v[140:143], v[214:217], v[8:11]
	v_mfma_i32_16x16x64_i8 v[52:55], v[162:165], v[186:189], v[52:55]
	v_mfma_i32_16x16x64_i8 v[48:51], v[170:173], v[186:189], v[48:51]
	v_mfma_i32_16x16x64_i8 v[36:39], v[162:165], v[194:197], v[36:39]
	v_mfma_i32_16x16x64_i8 v[32:35], v[170:173], v[194:197], v[32:35]
	v_mfma_i32_16x16x64_i8 v[20:23], v[162:165], v[202:205], v[20:23]
	v_mfma_i32_16x16x64_i8 v[16:19], v[170:173], v[202:205], v[16:19]
	v_mfma_i32_16x16x64_i8 v[4:7], v[162:165], v[210:213], v[4:7]
	v_mfma_i32_16x16x64_i8 v[0:3], v[170:173], v[210:213], v[0:3]
	v_mfma_i32_16x16x64_i8 v[52:55], v[166:169], v[190:193], v[52:55]
	v_mfma_i32_16x16x64_i8 v[48:51], v[174:177], v[190:193], v[48:51]
	v_mfma_i32_16x16x64_i8 v[36:39], v[166:169], v[198:201], v[36:39]
	v_mfma_i32_16x16x64_i8 v[32:35], v[174:177], v[198:201], v[32:35]
	v_mfma_i32_16x16x64_i8 v[20:23], v[166:169], v[206:209], v[20:23]
	v_mfma_i32_16x16x64_i8 v[16:19], v[174:177], v[206:209], v[16:19]
	v_mfma_i32_16x16x64_i8 v[4:7], v[166:169], v[214:217], v[4:7]
	v_mfma_i32_16x16x64_i8 v[0:3], v[174:177], v[214:217], v[0:3]
	s_barrier
	s_add_i32 s53, s53, 2
	s_add_u32 s51, s51, 0x100
	s_addc_u32 s52, s52, 0
	s_add_u32 s28, s28, 0x100
	s_addc_u32 s29, s29, 0
	s_cmpk_gt_u32 s53, 0x7d
	s_cbranch_scc0 .LBB0_1841
	s_setprio 0
	s_and_b64 vcc, exec, s[12:13]
	s_cbranch_vccz .LBB0_1844
	s_barrier

	.amdhsa_kernel _Z8yoco_fwd4Args
		.amdhsa_group_segment_fixed_size 0
		.amdhsa_private_segment_fixed_size 0
		.amdhsa_kernarg_size 440
		.amdhsa_user_sgpr_count 2
		.amdhsa_user_sgpr_dispatch_ptr 0
		.amdhsa_user_sgpr_queue_ptr 0
		.amdhsa_user_sgpr_kernarg_segment_ptr 1
		.amdhsa_user_sgpr_dispatch_id 0
		.amdhsa_user_sgpr_kernarg_preload_length 0
		.amdhsa_user_sgpr_kernarg_preload_offset 0
		.amdhsa_user_sgpr_private_segment_size 0
		.amdhsa_uses_dynamic_stack 0
		.amdhsa_enable_private_segment 0
		.amdhsa_system_sgpr_workgroup_id_x 1
		.amdhsa_system_sgpr_workgroup_id_y 0
		.amdhsa_system_sgpr_workgroup_id_z 0
		.amdhsa_system_sgpr_workgroup_info 0
		.amdhsa_system_vgpr_workitem_id 0
		.amdhsa_next_free_vgpr 256
		.amdhsa_next_free_sgpr 102
		.amdhsa_accum_offset 256
		.amdhsa_reserve_vcc 1
		.amdhsa_float_round_mode_32 0
		.amdhsa_float_round_mode_16_64 0
		.amdhsa_float_denorm_mode_32 3
		.amdhsa_float_denorm_mode_16_64 3
		.amdhsa_dx10_clamp 1
		.amdhsa_ieee_mode 1
		.amdhsa_fp16_overflow 0
		.amdhsa_tg_split 0
		.amdhsa_exception_fp_ieee_invalid_op 0
		.amdhsa_exception_fp_denorm_src 0
		.amdhsa_exception_fp_ieee_div_zero 0
		.amdhsa_exception_fp_ieee_overflow 0
		.amdhsa_exception_fp_ieee_underflow 0
		.amdhsa_exception_fp_ieee_inexact 0
		.amdhsa_exception_int_div_zero 0
	.end_amdhsa_kernel

.Lfunc_end0:
	.size	_Z8yoco_fwd4Args, .Lfunc_end0-_Z8yoco_fwd4Args
	.set _Z8yoco_fwd4Args.num_vgpr, 256
	.set _Z8yoco_fwd4Args.num_agpr, 0
	.set _Z8yoco_fwd4Args.numbered_sgpr, 102
	.set _Z8yoco_fwd4Args.num_named_barrier, 0
	.set _Z8yoco_fwd4Args.private_seg_size, 0
	.set _Z8yoco_fwd4Args.uses_vcc, 1
	.set _Z8yoco_fwd4Args.uses_flat_scratch, 0
	.set _Z8yoco_fwd4Args.has_dyn_sized_stack, 0
	.set _Z8yoco_fwd4Args.has_recursion, 0
	.set _Z8yoco_fwd4Args.has_indirect_call, 0

amdhsa.kernels:
  - .agpr_count:     0
    .args:
      - .offset:         0
        .size:           184
        .value_kind:     by_value
      - .offset:         184
        .size:           4
        .value_kind:     hidden_block_count_x
      - .offset:         188
        .size:           4
        .value_kind:     hidden_block_count_y
      - .offset:         192
        .size:           4
        .value_kind:     hidden_block_count_z
      - .offset:         196
        .size:           2
        .value_kind:     hidden_group_size_x
      - .offset:         198
        .size:           2
        .value_kind:     hidden_group_size_y
      - .offset:         200
        .size:           2
        .value_kind:     hidden_group_size_z
      - .offset:         202
        .size:           2
        .value_kind:     hidden_remainder_x
      - .offset:         204
        .size:           2
        .value_kind:     hidden_remainder_y
      - .offset:         206
        .size:           2
        .value_kind:     hidden_remainder_z
      - .offset:         224
        .size:           8
        .value_kind:     hidden_global_offset_x
      - .offset:         232
        .size:           8
        .value_kind:     hidden_global_offset_y
      - .offset:         240
        .size:           8
        .value_kind:     hidden_global_offset_z
      - .offset:         248
        .size:           2
        .value_kind:     hidden_grid_dims
      - .offset:         304
        .size:           4
        .value_kind:     hidden_dynamic_lds_size
    .group_segment_fixed_size: 0
    .kernarg_segment_align: 8
    .kernarg_segment_size: 440
    .language:       OpenCL C
    .language_version:
      - 2
      - 0
    .max_flat_workgroup_size: 512
    .name:           _Z8yoco_fwd4Args
    .private_segment_fixed_size: 0
    .sgpr_count:     108
    .sgpr_spill_count: 108
    .symbol:         _Z8yoco_fwd4Args.kd
    .uniform_work_group_size: 1
    .uses_dynamic_stack: false
    .vgpr_count:     256
    .vgpr_spill_count: 0
    .wavefront_size: 64
